# dead-code removal: hipcc zeroes the 128 accumulators twice per GEMM tile (header + preheader); the second, redundant run of 126 v_mov removed at 11 sites
# speedup vs baseline: 1.0011x; 1.0011x over previous
; #define PG8_BAR __builtin_amdgcn_s_barrier()
; template <class Epi, class Sched>
; __device__ __forceinline__ void gemm_phase(LAS unsigned char* lds, const Gemm g, const Sched& S, const Epi& E, const int wave_) {
;     ...
;         const bool has_next = S.next(ui + 1, nxt);
;         const char* nA = has_next ? (const char*)g.A + nxt.aoff : cA; const char* nB = has_next ? (const char*)g.Bt + nxt.boff : cB;
; #pragma unroll 1
;         for (int t = 0; t < nt; t += 2) {
;             if constexpr (Epi::HOOK) { if (t == 8 || t == 16) { E.hook(acc, cur, t >> 3, wr, wc, fr, fq); PG8_WAIT_V(0); } }
;             const bool last = (t == nt - 2);
;             const char* a1 = cA + (size_t)(t + 1) * kstep;
;             const char* a2 = last ? nA : cA + (size_t)(t + 2) * kstep; const char* b2 = last ? nB : cB + (size_t)(t + 2) * kstep;
;             const char* a3 = a2 + kstep; const char* b3 = b2 + kstep;
;             PG8_LDB(B0, 0, 0); PG8_LDB(B1, 0, 1); PG8_SCHED; PG8_LDA(At, 0, 0); PG8_STAGE(PG8_SA(1, 1), a1 + hstepA, voffA);
;             PG8_WAIT_V(8); PG8_WAIT_L(0); PG8_BAR; PG8_MMA(0, 0, At, B0); PG8_MMA(0, 1, At, B1); PG8_BAR; PG8_SCHED;
;             PG8_LDA(At, 0, 1); PG8_STAGE(PG8_SB(0, 0), b2, voffB); PG8_STAGE(PG8_SB(0, 1), b2 + hstepB, voffB); PG8_STAGE(PG8_SA(0, 0), a2, voffA);
;             PG8_WAIT_V(8); PG8_WAIT_L(0); PG8_BAR; PG8_MMA(1, 0, At, B0); PG8_MMA(1, 1, At, B1); PG8_BAR; PG8_SCHED;
;             PG8_LDB(B0, 1, 0); PG8_LDB(B1, 1, 1); PG8_SCHED; PG8_LDA(At, 1, 0); PG8_STAGE(PG8_SA(0, 1), a2 + hstepA, voffA);
;             PG8_WAIT_V(8); PG8_WAIT_L(0); PG8_BAR; PG8_MMA(0, 0, At, B0); PG8_MMA(0, 1, At, B1); PG8_BAR; PG8_SCHED;
;             PG8_LDA(At, 1, 1); PG8_STAGE(PG8_SB(1, 0), b3, voffB); PG8_STAGE(PG8_SB(1, 1), b3 + hstepB, voffB); PG8_STAGE(PG8_SA(1, 0), a3, voffA);
;             PG8_WAIT_V(8); PG8_WAIT_L(0); PG8_BAR; PG8_MMA(1, 0, At, B0); PG8_MMA(1, 1, At, B1); PG8_BAR; PG8_SCHED;
;         }
;         if (wr == 0) PG8_BAR;
;         E(acc, cur, wr, wc, fr, fq);
;         if (!has_next) break;
; #pragma unroll
;         for (int a = 0; a < 2; ++a)
; #pragma unroll
;             for (int b = 0; b < 2; ++b)
; #pragma unroll
;                 for (int m = 0; m < 4; ++m)
; #pragma unroll
;                     for (int n = 0; n < 2; ++n) acc[a][b][m][n] = (f32x4){0.f, 0.f, 0.f, 0.f};
;         cur = nxt; cA = nA; cB = nB; ++ui;
.LBB0_181:
	s_add_u32 s64, s34, s60
	s_addc_u32 s65, s35, s61
	s_add_u32 s66, s30, s62
	v_mov_b32_e32 v123, 0
	s_addc_u32 s67, s31, s63
	s_andn2_b64 vcc, exec, s[48:49]
	v_mov_b32_e32 v122, v123
	v_mov_b32_e32 v121, v123
	v_mov_b32_e32 v120, v123
	v_mov_b32_e32 v127, v123
	v_mov_b32_e32 v126, v123
	v_mov_b32_e32 v125, v123
	v_mov_b32_e32 v124, v123
	v_mov_b32_e32 v111, v123
	v_mov_b32_e32 v110, v123
	v_mov_b32_e32 v109, v123
	v_mov_b32_e32 v108, v123
	v_mov_b32_e32 v107, v123
	v_mov_b32_e32 v106, v123
	v_mov_b32_e32 v105, v123
	v_mov_b32_e32 v104, v123
	v_mov_b32_e32 v95, v123
	v_mov_b32_e32 v94, v123
	v_mov_b32_e32 v93, v123
	v_mov_b32_e32 v92, v123
	v_mov_b32_e32 v91, v123
	v_mov_b32_e32 v90, v123
	v_mov_b32_e32 v89, v123
	v_mov_b32_e32 v88, v123
	v_mov_b32_e32 v79, v123
	v_mov_b32_e32 v78, v123
	v_mov_b32_e32 v77, v123
	v_mov_b32_e32 v76, v123
	v_mov_b32_e32 v75, v123
	v_mov_b32_e32 v74, v123
	v_mov_b32_e32 v73, v123
	v_mov_b32_e32 v72, v123
	v_mov_b32_e32 v119, v123
	v_mov_b32_e32 v118, v123
	v_mov_b32_e32 v117, v123
	v_mov_b32_e32 v116, v123
	v_mov_b32_e32 v115, v123
	v_mov_b32_e32 v114, v123
	v_mov_b32_e32 v113, v123
	v_mov_b32_e32 v112, v123
	v_mov_b32_e32 v103, v123
	v_mov_b32_e32 v102, v123
	v_mov_b32_e32 v101, v123
	v_mov_b32_e32 v100, v123
	v_mov_b32_e32 v99, v123
	v_mov_b32_e32 v98, v123
	v_mov_b32_e32 v97, v123
	v_mov_b32_e32 v96, v123
	v_mov_b32_e32 v87, v123
	v_mov_b32_e32 v86, v123
	v_mov_b32_e32 v85, v123
	v_mov_b32_e32 v84, v123
	v_mov_b32_e32 v83, v123
	v_mov_b32_e32 v82, v123
	v_mov_b32_e32 v81, v123
	v_mov_b32_e32 v80, v123
	v_mov_b32_e32 v71, v123
	v_mov_b32_e32 v70, v123
	v_mov_b32_e32 v69, v123
	v_mov_b32_e32 v68, v123
	v_mov_b32_e32 v67, v123
	v_mov_b32_e32 v66, v123
	v_mov_b32_e32 v65, v123
	v_mov_b32_e32 v64, v123
	v_mov_b32_e32 v63, v123
	v_mov_b32_e32 v62, v123
	v_mov_b32_e32 v61, v123
	v_mov_b32_e32 v60, v123
	v_mov_b32_e32 v59, v123
	v_mov_b32_e32 v58, v123
	v_mov_b32_e32 v57, v123
	v_mov_b32_e32 v56, v123
	v_mov_b32_e32 v47, v123
	v_mov_b32_e32 v46, v123
	v_mov_b32_e32 v45, v123
	v_mov_b32_e32 v44, v123
	v_mov_b32_e32 v43, v123
	v_mov_b32_e32 v42, v123
	v_mov_b32_e32 v41, v123
	v_mov_b32_e32 v40, v123
	v_mov_b32_e32 v31, v123
	v_mov_b32_e32 v30, v123
	v_mov_b32_e32 v29, v123
	v_mov_b32_e32 v28, v123
	v_mov_b32_e32 v27, v123
	v_mov_b32_e32 v26, v123
	v_mov_b32_e32 v25, v123
	v_mov_b32_e32 v24, v123
	v_mov_b32_e32 v15, v123
	v_mov_b32_e32 v14, v123
	v_mov_b32_e32 v13, v123
	v_mov_b32_e32 v12, v123
	v_mov_b32_e32 v11, v123
	v_mov_b32_e32 v10, v123
	v_mov_b32_e32 v9, v123
	v_mov_b32_e32 v8, v123
	v_mov_b32_e32 v55, v123
	v_mov_b32_e32 v54, v123
	v_mov_b32_e32 v53, v123
	v_mov_b32_e32 v52, v123
	v_mov_b32_e32 v51, v123
	v_mov_b32_e32 v50, v123
	v_mov_b32_e32 v49, v123
	v_mov_b32_e32 v48, v123
	v_mov_b32_e32 v39, v123
	v_mov_b32_e32 v38, v123
	v_mov_b32_e32 v37, v123
	v_mov_b32_e32 v36, v123
	v_mov_b32_e32 v35, v123
	v_mov_b32_e32 v34, v123
	v_mov_b32_e32 v33, v123
	v_mov_b32_e32 v32, v123
	v_mov_b32_e32 v23, v123
	v_mov_b32_e32 v22, v123
	v_mov_b32_e32 v21, v123
	v_mov_b32_e32 v20, v123
	v_mov_b32_e32 v19, v123
	v_mov_b32_e32 v18, v123
	v_mov_b32_e32 v17, v123
	v_mov_b32_e32 v16, v123
	v_mov_b32_e32 v7, v123
	v_mov_b32_e32 v6, v123
	v_mov_b32_e32 v5, v123
	v_mov_b32_e32 v4, v123
	v_mov_b32_e32 v3, v123
	v_mov_b32_e32 v2, v123
	v_mov_b32_e32 v1, v123
	v_mov_b32_e32 v0, v123
	s_cbranch_vccnz .LBB0_184
	s_and_b64 s[70:71], s[4:5], exec
	s_cselect_b32 s7, s65, s69
	s_cselect_b32 s38, s64, s68
	s_cselect_b32 s57, s67, s9
	s_cselect_b32 s59, s66, s8
	s_add_u32 s72, s8, 0x100
	s_addc_u32 s73, s9, 0
	s_add_u32 s8, s68, 0x40080
	v_mov_b32_e32 v0, 0
	s_addc_u32 s9, s69, 0
	s_mov_b32 s68, 0

; #define PG8_BAR __builtin_amdgcn_s_barrier()
; template <class Epi, class Sched>
; __device__ __forceinline__ void gemm_phase(LAS unsigned char* lds, const Gemm g, const Sched& S, const Epi& E, const int wave_) {
;     ...
;         const bool has_next = S.next(ui + 1, nxt);
;         const char* nA = has_next ? (const char*)g.A + nxt.aoff : cA; const char* nB = has_next ? (const char*)g.Bt + nxt.boff : cB;
; #pragma unroll 1
;         for (int t = 0; t < nt; t += 2) {
;             if constexpr (Epi::HOOK) { if (t == 8 || t == 16) { E.hook(acc, cur, t >> 3, wr, wc, fr, fq); PG8_WAIT_V(0); } }
;             const bool last = (t == nt - 2);
;             const char* a1 = cA + (size_t)(t + 1) * kstep;
;             const char* a2 = last ? nA : cA + (size_t)(t + 2) * kstep; const char* b2 = last ? nB : cB + (size_t)(t + 2) * kstep;
;             const char* a3 = a2 + kstep; const char* b3 = b2 + kstep;
;             PG8_LDB(B0, 0, 0); PG8_LDB(B1, 0, 1); PG8_SCHED; PG8_LDA(At, 0, 0); PG8_STAGE(PG8_SA(1, 1), a1 + hstepA, voffA);
;             PG8_WAIT_V(8); PG8_WAIT_L(0); PG8_BAR; PG8_MMA(0, 0, At, B0); PG8_MMA(0, 1, At, B1); PG8_BAR; PG8_SCHED;
;             PG8_LDA(At, 0, 1); PG8_STAGE(PG8_SB(0, 0), b2, voffB); PG8_STAGE(PG8_SB(0, 1), b2 + hstepB, voffB); PG8_STAGE(PG8_SA(0, 0), a2, voffA);
;             PG8_WAIT_V(8); PG8_WAIT_L(0); PG8_BAR; PG8_MMA(1, 0, At, B0); PG8_MMA(1, 1, At, B1); PG8_BAR; PG8_SCHED;
;             PG8_LDB(B0, 1, 0); PG8_LDB(B1, 1, 1); PG8_SCHED; PG8_LDA(At, 1, 0); PG8_STAGE(PG8_SA(0, 1), a2 + hstepA, voffA);
;             PG8_WAIT_V(8); PG8_WAIT_L(0); PG8_BAR; PG8_MMA(0, 0, At, B0); PG8_MMA(0, 1, At, B1); PG8_BAR; PG8_SCHED;
;             PG8_LDA(At, 1, 1); PG8_STAGE(PG8_SB(1, 0), b3, voffB); PG8_STAGE(PG8_SB(1, 1), b3 + hstepB, voffB); PG8_STAGE(PG8_SA(1, 0), a3, voffA);
;             PG8_WAIT_V(8); PG8_WAIT_L(0); PG8_BAR; PG8_MMA(1, 0, At, B0); PG8_MMA(1, 1, At, B1); PG8_BAR; PG8_SCHED;
;         }
;         if (wr == 0) PG8_BAR;
;         E(acc, cur, wr, wc, fr, fq);
;         if (!has_next) break;
; #pragma unroll
;         for (int a = 0; a < 2; ++a)
; #pragma unroll
;             for (int b = 0; b < 2; ++b)
; #pragma unroll
;                 for (int m = 0; m < 4; ++m)
; #pragma unroll
;                     for (int n = 0; n < 2; ++n) acc[a][b][m][n] = (f32x4){0.f, 0.f, 0.f, 0.f};
;         cur = nxt; cA = nA; cB = nB; ++ui;
.LBB0_522:
	s_add_u32 s50, s10, s46
	s_addc_u32 s51, s11, s47
	s_add_u32 s52, s29, s48
	v_mov_b32_e32 v123, 0
	s_addc_u32 s53, s60, s49
	s_andn2_b64 vcc, exec, s[36:37]
	v_mov_b32_e32 v122, v123
	v_mov_b32_e32 v121, v123
	v_mov_b32_e32 v120, v123
	v_mov_b32_e32 v127, v123
	v_mov_b32_e32 v126, v123
	v_mov_b32_e32 v125, v123
	v_mov_b32_e32 v124, v123
	v_mov_b32_e32 v111, v123
	v_mov_b32_e32 v110, v123
	v_mov_b32_e32 v109, v123
	v_mov_b32_e32 v108, v123
	v_mov_b32_e32 v107, v123
	v_mov_b32_e32 v106, v123
	v_mov_b32_e32 v105, v123
	v_mov_b32_e32 v104, v123
	v_mov_b32_e32 v95, v123
	v_mov_b32_e32 v94, v123
	v_mov_b32_e32 v93, v123
	v_mov_b32_e32 v92, v123
	v_mov_b32_e32 v91, v123
	v_mov_b32_e32 v90, v123
	v_mov_b32_e32 v89, v123
	v_mov_b32_e32 v88, v123
	v_mov_b32_e32 v79, v123
	v_mov_b32_e32 v78, v123
	v_mov_b32_e32 v77, v123
	v_mov_b32_e32 v76, v123
	v_mov_b32_e32 v75, v123
	v_mov_b32_e32 v74, v123
	v_mov_b32_e32 v73, v123
	v_mov_b32_e32 v72, v123
	v_mov_b32_e32 v119, v123
	v_mov_b32_e32 v118, v123
	v_mov_b32_e32 v117, v123
	v_mov_b32_e32 v116, v123
	v_mov_b32_e32 v115, v123
	v_mov_b32_e32 v114, v123
	v_mov_b32_e32 v113, v123
	v_mov_b32_e32 v112, v123
	v_mov_b32_e32 v103, v123
	v_mov_b32_e32 v102, v123
	v_mov_b32_e32 v101, v123
	v_mov_b32_e32 v100, v123
	v_mov_b32_e32 v99, v123
	v_mov_b32_e32 v98, v123
	v_mov_b32_e32 v97, v123
	v_mov_b32_e32 v96, v123
	v_mov_b32_e32 v87, v123
	v_mov_b32_e32 v86, v123
	v_mov_b32_e32 v85, v123
	v_mov_b32_e32 v84, v123
	v_mov_b32_e32 v83, v123
	v_mov_b32_e32 v82, v123
	v_mov_b32_e32 v81, v123
	v_mov_b32_e32 v80, v123
	v_mov_b32_e32 v71, v123
	v_mov_b32_e32 v70, v123
	v_mov_b32_e32 v69, v123
	v_mov_b32_e32 v68, v123
	v_mov_b32_e32 v67, v123
	v_mov_b32_e32 v66, v123
	v_mov_b32_e32 v65, v123
	v_mov_b32_e32 v64, v123
	v_mov_b32_e32 v63, v123
	v_mov_b32_e32 v62, v123
	v_mov_b32_e32 v61, v123
	v_mov_b32_e32 v60, v123
	v_mov_b32_e32 v59, v123
	v_mov_b32_e32 v58, v123
	v_mov_b32_e32 v57, v123
	v_mov_b32_e32 v56, v123
	v_mov_b32_e32 v47, v123
	v_mov_b32_e32 v46, v123
	v_mov_b32_e32 v45, v123
	v_mov_b32_e32 v44, v123
	v_mov_b32_e32 v43, v123
	v_mov_b32_e32 v42, v123
	v_mov_b32_e32 v41, v123
	v_mov_b32_e32 v40, v123
	v_mov_b32_e32 v31, v123
	v_mov_b32_e32 v30, v123
	v_mov_b32_e32 v29, v123
	v_mov_b32_e32 v28, v123
	v_mov_b32_e32 v27, v123
	v_mov_b32_e32 v26, v123
	v_mov_b32_e32 v25, v123
	v_mov_b32_e32 v24, v123
	v_mov_b32_e32 v15, v123
	v_mov_b32_e32 v14, v123
	v_mov_b32_e32 v13, v123
	v_mov_b32_e32 v12, v123
	v_mov_b32_e32 v11, v123
	v_mov_b32_e32 v10, v123
	v_mov_b32_e32 v9, v123
	v_mov_b32_e32 v8, v123
	v_mov_b32_e32 v55, v123
	v_mov_b32_e32 v54, v123
	v_mov_b32_e32 v53, v123
	v_mov_b32_e32 v52, v123
	v_mov_b32_e32 v51, v123
	v_mov_b32_e32 v50, v123
	v_mov_b32_e32 v49, v123
	v_mov_b32_e32 v48, v123
	v_mov_b32_e32 v39, v123
	v_mov_b32_e32 v38, v123
	v_mov_b32_e32 v37, v123
	v_mov_b32_e32 v36, v123
	v_mov_b32_e32 v35, v123
	v_mov_b32_e32 v34, v123
	v_mov_b32_e32 v33, v123
	v_mov_b32_e32 v32, v123
	v_mov_b32_e32 v23, v123
	v_mov_b32_e32 v22, v123
	v_mov_b32_e32 v21, v123
	v_mov_b32_e32 v20, v123
	v_mov_b32_e32 v19, v123
	v_mov_b32_e32 v18, v123
	v_mov_b32_e32 v17, v123
	v_mov_b32_e32 v16, v123
	v_mov_b32_e32 v7, v123
	v_mov_b32_e32 v6, v123
	v_mov_b32_e32 v5, v123
	v_mov_b32_e32 v4, v123
	v_mov_b32_e32 v3, v123
	v_mov_b32_e32 v2, v123
	v_mov_b32_e32 v1, v123
	v_mov_b32_e32 v0, v123
	s_cbranch_vccnz .LBB0_525
	s_and_b64 s[58:59], s[44:45], exec
	s_cselect_b32 s43, s51, s57
	s_cselect_b32 s73, s50, s56
	s_cselect_b32 s74, s53, s55
	s_cselect_b32 s75, s52, s54
	s_add_u32 s76, s54, 0x100
	s_addc_u32 s77, s55, 0
	s_add_u32 s54, s56, 0x40080
	v_mov_b32_e32 v0, 0
	s_addc_u32 s55, s57, 0
	s_mov_b32 s56, 0

; #define PG8_BAR __builtin_amdgcn_s_barrier()
; template <class Epi, class Sched>
; __device__ __forceinline__ void gemm_phase(LAS unsigned char* lds, const Gemm g, const Sched& S, const Epi& E, const int wave_) {
;     ...
;         const bool has_next = S.next(ui + 1, nxt);
;         const char* nA = has_next ? (const char*)g.A + nxt.aoff : cA; const char* nB = has_next ? (const char*)g.Bt + nxt.boff : cB;
; #pragma unroll 1
;         for (int t = 0; t < nt; t += 2) {
;             if constexpr (Epi::HOOK) { if (t == 8 || t == 16) { E.hook(acc, cur, t >> 3, wr, wc, fr, fq); PG8_WAIT_V(0); } }
;             const bool last = (t == nt - 2);
;             const char* a1 = cA + (size_t)(t + 1) * kstep;
;             const char* a2 = last ? nA : cA + (size_t)(t + 2) * kstep; const char* b2 = last ? nB : cB + (size_t)(t + 2) * kstep;
;             const char* a3 = a2 + kstep; const char* b3 = b2 + kstep;
;             PG8_LDB(B0, 0, 0); PG8_LDB(B1, 0, 1); PG8_SCHED; PG8_LDA(At, 0, 0); PG8_STAGE(PG8_SA(1, 1), a1 + hstepA, voffA);
;             PG8_WAIT_V(8); PG8_WAIT_L(0); PG8_BAR; PG8_MMA(0, 0, At, B0); PG8_MMA(0, 1, At, B1); PG8_BAR; PG8_SCHED;
;             PG8_LDA(At, 0, 1); PG8_STAGE(PG8_SB(0, 0), b2, voffB); PG8_STAGE(PG8_SB(0, 1), b2 + hstepB, voffB); PG8_STAGE(PG8_SA(0, 0), a2, voffA);
;             PG8_WAIT_V(8); PG8_WAIT_L(0); PG8_BAR; PG8_MMA(1, 0, At, B0); PG8_MMA(1, 1, At, B1); PG8_BAR; PG8_SCHED;
;             PG8_LDB(B0, 1, 0); PG8_LDB(B1, 1, 1); PG8_SCHED; PG8_LDA(At, 1, 0); PG8_STAGE(PG8_SA(0, 1), a2 + hstepA, voffA);
;             PG8_WAIT_V(8); PG8_WAIT_L(0); PG8_BAR; PG8_MMA(0, 0, At, B0); PG8_MMA(0, 1, At, B1); PG8_BAR; PG8_SCHED;
;             PG8_LDA(At, 1, 1); PG8_STAGE(PG8_SB(1, 0), b3, voffB); PG8_STAGE(PG8_SB(1, 1), b3 + hstepB, voffB); PG8_STAGE(PG8_SA(1, 0), a3, voffA);
;             PG8_WAIT_V(8); PG8_WAIT_L(0); PG8_BAR; PG8_MMA(1, 0, At, B0); PG8_MMA(1, 1, At, B1); PG8_BAR; PG8_SCHED;
;         }
;         if (wr == 0) PG8_BAR;
;         E(acc, cur, wr, wc, fr, fq);
;         if (!has_next) break;
; #pragma unroll
;         for (int a = 0; a < 2; ++a)
; #pragma unroll
;             for (int b = 0; b < 2; ++b)
; #pragma unroll
;                 for (int m = 0; m < 4; ++m)
; #pragma unroll
;                     for (int n = 0; n < 2; ++n) acc[a][b][m][n] = (f32x4){0.f, 0.f, 0.f, 0.f};
;         cur = nxt; cA = nA; cB = nB; ++ui;
.LBB0_547:
	s_add_u32 s50, s60, s46
	s_addc_u32 s51, s61, s47
	s_add_u32 s52, s10, s48
	v_mov_b32_e32 v123, 0
	s_addc_u32 s53, s11, s49
	s_andn2_b64 vcc, exec, s[8:9]
	v_mov_b32_e32 v122, v123
	v_mov_b32_e32 v121, v123
	v_mov_b32_e32 v120, v123
	v_mov_b32_e32 v127, v123
	v_mov_b32_e32 v126, v123
	v_mov_b32_e32 v125, v123
	v_mov_b32_e32 v124, v123
	v_mov_b32_e32 v111, v123
	v_mov_b32_e32 v110, v123
	v_mov_b32_e32 v109, v123
	v_mov_b32_e32 v108, v123
	v_mov_b32_e32 v107, v123
	v_mov_b32_e32 v106, v123
	v_mov_b32_e32 v105, v123
	v_mov_b32_e32 v104, v123
	v_mov_b32_e32 v95, v123
	v_mov_b32_e32 v94, v123
	v_mov_b32_e32 v93, v123
	v_mov_b32_e32 v92, v123
	v_mov_b32_e32 v91, v123
	v_mov_b32_e32 v90, v123
	v_mov_b32_e32 v89, v123
	v_mov_b32_e32 v88, v123
	v_mov_b32_e32 v79, v123
	v_mov_b32_e32 v78, v123
	v_mov_b32_e32 v77, v123
	v_mov_b32_e32 v76, v123
	v_mov_b32_e32 v75, v123
	v_mov_b32_e32 v74, v123
	v_mov_b32_e32 v73, v123
	v_mov_b32_e32 v72, v123
	v_mov_b32_e32 v119, v123
	v_mov_b32_e32 v118, v123
	v_mov_b32_e32 v117, v123
	v_mov_b32_e32 v116, v123
	v_mov_b32_e32 v115, v123
	v_mov_b32_e32 v114, v123
	v_mov_b32_e32 v113, v123
	v_mov_b32_e32 v112, v123
	v_mov_b32_e32 v103, v123
	v_mov_b32_e32 v102, v123
	v_mov_b32_e32 v101, v123
	v_mov_b32_e32 v100, v123
	v_mov_b32_e32 v99, v123
	v_mov_b32_e32 v98, v123
	v_mov_b32_e32 v97, v123
	v_mov_b32_e32 v96, v123
	v_mov_b32_e32 v87, v123
	v_mov_b32_e32 v86, v123
	v_mov_b32_e32 v85, v123
	v_mov_b32_e32 v84, v123
	v_mov_b32_e32 v83, v123
	v_mov_b32_e32 v82, v123
	v_mov_b32_e32 v81, v123
	v_mov_b32_e32 v80, v123
	v_mov_b32_e32 v71, v123
	v_mov_b32_e32 v70, v123
	v_mov_b32_e32 v69, v123
	v_mov_b32_e32 v68, v123
	v_mov_b32_e32 v67, v123
	v_mov_b32_e32 v66, v123
	v_mov_b32_e32 v65, v123
	v_mov_b32_e32 v64, v123
	v_mov_b32_e32 v63, v123
	v_mov_b32_e32 v62, v123
	v_mov_b32_e32 v61, v123
	v_mov_b32_e32 v60, v123
	v_mov_b32_e32 v59, v123
	v_mov_b32_e32 v58, v123
	v_mov_b32_e32 v57, v123
	v_mov_b32_e32 v56, v123
	v_mov_b32_e32 v47, v123
	v_mov_b32_e32 v46, v123
	v_mov_b32_e32 v45, v123
	v_mov_b32_e32 v44, v123
	v_mov_b32_e32 v43, v123
	v_mov_b32_e32 v42, v123
	v_mov_b32_e32 v41, v123
	v_mov_b32_e32 v40, v123
	v_mov_b32_e32 v31, v123
	v_mov_b32_e32 v30, v123
	v_mov_b32_e32 v29, v123
	v_mov_b32_e32 v28, v123
	v_mov_b32_e32 v27, v123
	v_mov_b32_e32 v26, v123
	v_mov_b32_e32 v25, v123
	v_mov_b32_e32 v24, v123
	v_mov_b32_e32 v15, v123
	v_mov_b32_e32 v14, v123
	v_mov_b32_e32 v13, v123
	v_mov_b32_e32 v12, v123
	v_mov_b32_e32 v11, v123
	v_mov_b32_e32 v10, v123
	v_mov_b32_e32 v9, v123
	v_mov_b32_e32 v8, v123
	v_mov_b32_e32 v55, v123
	v_mov_b32_e32 v54, v123
	v_mov_b32_e32 v53, v123
	v_mov_b32_e32 v52, v123
	v_mov_b32_e32 v51, v123
	v_mov_b32_e32 v50, v123
	v_mov_b32_e32 v49, v123
	v_mov_b32_e32 v48, v123
	v_mov_b32_e32 v39, v123
	v_mov_b32_e32 v38, v123
	v_mov_b32_e32 v37, v123
	v_mov_b32_e32 v36, v123
	v_mov_b32_e32 v35, v123
	v_mov_b32_e32 v34, v123
	v_mov_b32_e32 v33, v123
	v_mov_b32_e32 v32, v123
	v_mov_b32_e32 v23, v123
	v_mov_b32_e32 v22, v123
	v_mov_b32_e32 v21, v123
	v_mov_b32_e32 v20, v123
	v_mov_b32_e32 v19, v123
	v_mov_b32_e32 v18, v123
	v_mov_b32_e32 v17, v123
	v_mov_b32_e32 v16, v123
	v_mov_b32_e32 v7, v123
	v_mov_b32_e32 v6, v123
	v_mov_b32_e32 v5, v123
	v_mov_b32_e32 v4, v123
	v_mov_b32_e32 v3, v123
	v_mov_b32_e32 v2, v123
	v_mov_b32_e32 v1, v123
	v_mov_b32_e32 v0, v123
	s_cbranch_vccnz .LBB0_550
	s_and_b64 s[58:59], s[40:41], exec
	s_cselect_b32 s43, s51, s57
	s_cselect_b32 s45, s50, s56
	s_cselect_b32 s72, s53, s55
	s_cselect_b32 s73, s52, s54
	s_add_u32 s74, s54, 0x100
	s_addc_u32 s75, s55, 0
	s_add_u32 s54, s56, 0x40080
	v_mov_b32_e32 v0, 0
	s_addc_u32 s55, s57, 0
	s_mov_b32 s56, 0

; #define PG8_BAR __builtin_amdgcn_s_barrier()
; template <class Epi, class Sched>
; __device__ __forceinline__ void gemm_phase(LAS unsigned char* lds, const Gemm g, const Sched& S, const Epi& E, const int wave_) {
;     ...
;         const bool has_next = S.next(ui + 1, nxt);
;         const char* nA = has_next ? (const char*)g.A + nxt.aoff : cA; const char* nB = has_next ? (const char*)g.Bt + nxt.boff : cB;
; #pragma unroll 1
;         for (int t = 0; t < nt; t += 2) {
;             if constexpr (Epi::HOOK) { if (t == 8 || t == 16) { E.hook(acc, cur, t >> 3, wr, wc, fr, fq); PG8_WAIT_V(0); } }
;             const bool last = (t == nt - 2);
;             const char* a1 = cA + (size_t)(t + 1) * kstep;
;             const char* a2 = last ? nA : cA + (size_t)(t + 2) * kstep; const char* b2 = last ? nB : cB + (size_t)(t + 2) * kstep;
;             const char* a3 = a2 + kstep; const char* b3 = b2 + kstep;
;             PG8_LDB(B0, 0, 0); PG8_LDB(B1, 0, 1); PG8_SCHED; PG8_LDA(At, 0, 0); PG8_STAGE(PG8_SA(1, 1), a1 + hstepA, voffA);
;             PG8_WAIT_V(8); PG8_WAIT_L(0); PG8_BAR; PG8_MMA(0, 0, At, B0); PG8_MMA(0, 1, At, B1); PG8_BAR; PG8_SCHED;
;             PG8_LDA(At, 0, 1); PG8_STAGE(PG8_SB(0, 0), b2, voffB); PG8_STAGE(PG8_SB(0, 1), b2 + hstepB, voffB); PG8_STAGE(PG8_SA(0, 0), a2, voffA);
;             PG8_WAIT_V(8); PG8_WAIT_L(0); PG8_BAR; PG8_MMA(1, 0, At, B0); PG8_MMA(1, 1, At, B1); PG8_BAR; PG8_SCHED;
;             PG8_LDB(B0, 1, 0); PG8_LDB(B1, 1, 1); PG8_SCHED; PG8_LDA(At, 1, 0); PG8_STAGE(PG8_SA(0, 1), a2 + hstepA, voffA);
;             PG8_WAIT_V(8); PG8_WAIT_L(0); PG8_BAR; PG8_MMA(0, 0, At, B0); PG8_MMA(0, 1, At, B1); PG8_BAR; PG8_SCHED;
;             PG8_LDA(At, 1, 1); PG8_STAGE(PG8_SB(1, 0), b3, voffB); PG8_STAGE(PG8_SB(1, 1), b3 + hstepB, voffB); PG8_STAGE(PG8_SA(1, 0), a3, voffA);
;             PG8_WAIT_V(8); PG8_WAIT_L(0); PG8_BAR; PG8_MMA(1, 0, At, B0); PG8_MMA(1, 1, At, B1); PG8_BAR; PG8_SCHED;
;         }
;         if (wr == 0) PG8_BAR;
;         E(acc, cur, wr, wc, fr, fq);
;         if (!has_next) break;
; #pragma unroll
;         for (int a = 0; a < 2; ++a)
; #pragma unroll
;             for (int b = 0; b < 2; ++b)
; #pragma unroll
;                 for (int m = 0; m < 4; ++m)
; #pragma unroll
;                     for (int n = 0; n < 2; ++n) acc[a][b][m][n] = (f32x4){0.f, 0.f, 0.f, 0.f};
;         cur = nxt; cA = nA; cB = nB; ++ui;
.LBB0_615:
	s_add_u32 s42, s10, s40
	s_addc_u32 s43, s11, s41
	s_add_u32 s44, s24, s30
	v_mov_b32_e32 v127, 0
	s_addc_u32 s45, s25, s31
	s_and_b64 vcc, exec, s[4:5]
	v_mov_b32_e32 v126, v127
	v_mov_b32_e32 v125, v127
	v_mov_b32_e32 v124, v127
	v_mov_b32_e32 v123, v127
	v_mov_b32_e32 v122, v127
	v_mov_b32_e32 v121, v127
	v_mov_b32_e32 v120, v127
	v_mov_b32_e32 v111, v127
	v_mov_b32_e32 v110, v127
	v_mov_b32_e32 v109, v127
	v_mov_b32_e32 v108, v127
	v_mov_b32_e32 v107, v127
	v_mov_b32_e32 v106, v127
	v_mov_b32_e32 v105, v127
	v_mov_b32_e32 v104, v127
	v_mov_b32_e32 v95, v127
	v_mov_b32_e32 v94, v127
	v_mov_b32_e32 v93, v127
	v_mov_b32_e32 v92, v127
	v_mov_b32_e32 v91, v127
	v_mov_b32_e32 v90, v127
	v_mov_b32_e32 v89, v127
	v_mov_b32_e32 v88, v127
	v_mov_b32_e32 v79, v127
	v_mov_b32_e32 v78, v127
	v_mov_b32_e32 v77, v127
	v_mov_b32_e32 v76, v127
	v_mov_b32_e32 v75, v127
	v_mov_b32_e32 v74, v127
	v_mov_b32_e32 v73, v127
	v_mov_b32_e32 v72, v127
	v_mov_b32_e32 v119, v127
	v_mov_b32_e32 v118, v127
	v_mov_b32_e32 v117, v127
	v_mov_b32_e32 v116, v127
	v_mov_b32_e32 v115, v127
	v_mov_b32_e32 v114, v127
	v_mov_b32_e32 v113, v127
	v_mov_b32_e32 v112, v127
	v_mov_b32_e32 v103, v127
	v_mov_b32_e32 v102, v127
	v_mov_b32_e32 v101, v127
	v_mov_b32_e32 v100, v127
	v_mov_b32_e32 v99, v127
	v_mov_b32_e32 v98, v127
	v_mov_b32_e32 v97, v127
	v_mov_b32_e32 v96, v127
	v_mov_b32_e32 v87, v127
	v_mov_b32_e32 v86, v127
	v_mov_b32_e32 v85, v127
	v_mov_b32_e32 v84, v127
	v_mov_b32_e32 v83, v127
	v_mov_b32_e32 v82, v127
	v_mov_b32_e32 v81, v127
	v_mov_b32_e32 v80, v127
	v_mov_b32_e32 v71, v127
	v_mov_b32_e32 v70, v127
	v_mov_b32_e32 v69, v127
	v_mov_b32_e32 v68, v127
	v_mov_b32_e32 v67, v127
	v_mov_b32_e32 v66, v127
	v_mov_b32_e32 v65, v127
	v_mov_b32_e32 v64, v127
	v_mov_b32_e32 v63, v127
	v_mov_b32_e32 v62, v127
	v_mov_b32_e32 v61, v127
	v_mov_b32_e32 v60, v127
	v_mov_b32_e32 v59, v127
	v_mov_b32_e32 v58, v127
	v_mov_b32_e32 v57, v127
	v_mov_b32_e32 v56, v127
	v_mov_b32_e32 v47, v127
	v_mov_b32_e32 v46, v127
	v_mov_b32_e32 v45, v127
	v_mov_b32_e32 v44, v127
	v_mov_b32_e32 v43, v127
	v_mov_b32_e32 v42, v127
	v_mov_b32_e32 v41, v127
	v_mov_b32_e32 v40, v127
	v_mov_b32_e32 v31, v127
	v_mov_b32_e32 v30, v127
	v_mov_b32_e32 v29, v127
	v_mov_b32_e32 v28, v127
	v_mov_b32_e32 v27, v127
	v_mov_b32_e32 v26, v127
	v_mov_b32_e32 v25, v127
	v_mov_b32_e32 v24, v127
	v_mov_b32_e32 v15, v127
	v_mov_b32_e32 v14, v127
	v_mov_b32_e32 v13, v127
	v_mov_b32_e32 v12, v127
	v_mov_b32_e32 v11, v127
	v_mov_b32_e32 v10, v127
	v_mov_b32_e32 v9, v127
	v_mov_b32_e32 v8, v127
	v_mov_b32_e32 v55, v127
	v_mov_b32_e32 v54, v127
	v_mov_b32_e32 v53, v127
	v_mov_b32_e32 v52, v127
	v_mov_b32_e32 v51, v127
	v_mov_b32_e32 v50, v127
	v_mov_b32_e32 v49, v127
	v_mov_b32_e32 v48, v127
	v_mov_b32_e32 v39, v127
	v_mov_b32_e32 v38, v127
	v_mov_b32_e32 v37, v127
	v_mov_b32_e32 v36, v127
	v_mov_b32_e32 v35, v127
	v_mov_b32_e32 v34, v127
	v_mov_b32_e32 v33, v127
	v_mov_b32_e32 v32, v127
	v_mov_b32_e32 v23, v127
	v_mov_b32_e32 v22, v127
	v_mov_b32_e32 v21, v127
	v_mov_b32_e32 v20, v127
	v_mov_b32_e32 v19, v127
	v_mov_b32_e32 v18, v127
	v_mov_b32_e32 v17, v127
	v_mov_b32_e32 v16, v127
	v_mov_b32_e32 v7, v127
	v_mov_b32_e32 v6, v127
	v_mov_b32_e32 v5, v127
	v_mov_b32_e32 v4, v127
	v_mov_b32_e32 v3, v127
	v_mov_b32_e32 v2, v127
	v_mov_b32_e32 v1, v127
	v_mov_b32_e32 v0, v127
	s_cbranch_vccnz .LBB0_618
	s_and_b64 s[50:51], s[6:7], exec
	s_cselect_b32 s66, s43, s49
	s_cselect_b32 s67, s42, s48
	s_cselect_b32 s68, s45, s47
	s_cselect_b32 s69, s44, s46
	s_add_u32 s70, s46, 0x100
	s_addc_u32 s71, s47, 0
	s_add_u32 s46, s48, 0x20080
	v_mov_b32_e32 v0, 0
	s_addc_u32 s47, s49, 0
	s_mov_b32 s48, 0

; #define PG8_BAR __builtin_amdgcn_s_barrier()
; template <class Epi, class Sched>
; __device__ __forceinline__ void gemm_phase(LAS unsigned char* lds, const Gemm g, const Sched& S, const Epi& E, const int wave_) {
;     ...
;         const bool has_next = S.next(ui + 1, nxt);
;         const char* nA = has_next ? (const char*)g.A + nxt.aoff : cA; const char* nB = has_next ? (const char*)g.Bt + nxt.boff : cB;
; #pragma unroll 1
;         for (int t = 0; t < nt; t += 2) {
;             if constexpr (Epi::HOOK) { if (t == 8 || t == 16) { E.hook(acc, cur, t >> 3, wr, wc, fr, fq); PG8_WAIT_V(0); } }
;             const bool last = (t == nt - 2);
;             const char* a1 = cA + (size_t)(t + 1) * kstep;
;             const char* a2 = last ? nA : cA + (size_t)(t + 2) * kstep; const char* b2 = last ? nB : cB + (size_t)(t + 2) * kstep;
;             const char* a3 = a2 + kstep; const char* b3 = b2 + kstep;
;             PG8_LDB(B0, 0, 0); PG8_LDB(B1, 0, 1); PG8_SCHED; PG8_LDA(At, 0, 0); PG8_STAGE(PG8_SA(1, 1), a1 + hstepA, voffA);
;             PG8_WAIT_V(8); PG8_WAIT_L(0); PG8_BAR; PG8_MMA(0, 0, At, B0); PG8_MMA(0, 1, At, B1); PG8_BAR; PG8_SCHED;
;             PG8_LDA(At, 0, 1); PG8_STAGE(PG8_SB(0, 0), b2, voffB); PG8_STAGE(PG8_SB(0, 1), b2 + hstepB, voffB); PG8_STAGE(PG8_SA(0, 0), a2, voffA);
;             PG8_WAIT_V(8); PG8_WAIT_L(0); PG8_BAR; PG8_MMA(1, 0, At, B0); PG8_MMA(1, 1, At, B1); PG8_BAR; PG8_SCHED;
;             PG8_LDB(B0, 1, 0); PG8_LDB(B1, 1, 1); PG8_SCHED; PG8_LDA(At, 1, 0); PG8_STAGE(PG8_SA(0, 1), a2 + hstepA, voffA);
;             PG8_WAIT_V(8); PG8_WAIT_L(0); PG8_BAR; PG8_MMA(0, 0, At, B0); PG8_MMA(0, 1, At, B1); PG8_BAR; PG8_SCHED;
;             PG8_LDA(At, 1, 1); PG8_STAGE(PG8_SB(1, 0), b3, voffB); PG8_STAGE(PG8_SB(1, 1), b3 + hstepB, voffB); PG8_STAGE(PG8_SA(1, 0), a3, voffA);
;             PG8_WAIT_V(8); PG8_WAIT_L(0); PG8_BAR; PG8_MMA(1, 0, At, B0); PG8_MMA(1, 1, At, B1); PG8_BAR; PG8_SCHED;
;         }
;         if (wr == 0) PG8_BAR;
;         E(acc, cur, wr, wc, fr, fq);
;         if (!has_next) break;
; #pragma unroll
;         for (int a = 0; a < 2; ++a)
; #pragma unroll
;             for (int b = 0; b < 2; ++b)
; #pragma unroll
;                 for (int m = 0; m < 4; ++m)
; #pragma unroll
;                     for (int n = 0; n < 2; ++n) acc[a][b][m][n] = (f32x4){0.f, 0.f, 0.f, 0.f};
;         cur = nxt; cA = nA; cB = nB; ++ui;
.LBB0_694:
	s_add_u32 s46, s24, s44
	s_addc_u32 s47, s25, s45
	s_add_u32 s48, s56, s42
	v_mov_b32_e32 v127, 0
	s_addc_u32 s49, s57, s43
	s_and_b64 vcc, exec, s[6:7]
	v_mov_b32_e32 v126, v127
	v_mov_b32_e32 v125, v127
	v_mov_b32_e32 v124, v127
	v_mov_b32_e32 v123, v127
	v_mov_b32_e32 v122, v127
	v_mov_b32_e32 v121, v127
	v_mov_b32_e32 v120, v127
	v_mov_b32_e32 v111, v127
	v_mov_b32_e32 v110, v127
	v_mov_b32_e32 v109, v127
	v_mov_b32_e32 v108, v127
	v_mov_b32_e32 v107, v127
	v_mov_b32_e32 v106, v127
	v_mov_b32_e32 v105, v127
	v_mov_b32_e32 v104, v127
	v_mov_b32_e32 v95, v127
	v_mov_b32_e32 v94, v127
	v_mov_b32_e32 v93, v127
	v_mov_b32_e32 v92, v127
	v_mov_b32_e32 v91, v127
	v_mov_b32_e32 v90, v127
	v_mov_b32_e32 v89, v127
	v_mov_b32_e32 v88, v127
	v_mov_b32_e32 v79, v127
	v_mov_b32_e32 v78, v127
	v_mov_b32_e32 v77, v127
	v_mov_b32_e32 v76, v127
	v_mov_b32_e32 v75, v127
	v_mov_b32_e32 v74, v127
	v_mov_b32_e32 v73, v127
	v_mov_b32_e32 v72, v127
	v_mov_b32_e32 v119, v127
	v_mov_b32_e32 v118, v127
	v_mov_b32_e32 v117, v127
	v_mov_b32_e32 v116, v127
	v_mov_b32_e32 v115, v127
	v_mov_b32_e32 v114, v127
	v_mov_b32_e32 v113, v127
	v_mov_b32_e32 v112, v127
	v_mov_b32_e32 v103, v127
	v_mov_b32_e32 v102, v127
	v_mov_b32_e32 v101, v127
	v_mov_b32_e32 v100, v127
	v_mov_b32_e32 v99, v127
	v_mov_b32_e32 v98, v127
	v_mov_b32_e32 v97, v127
	v_mov_b32_e32 v96, v127
	v_mov_b32_e32 v87, v127
	v_mov_b32_e32 v86, v127
	v_mov_b32_e32 v85, v127
	v_mov_b32_e32 v84, v127
	v_mov_b32_e32 v83, v127
	v_mov_b32_e32 v82, v127
	v_mov_b32_e32 v81, v127
	v_mov_b32_e32 v80, v127
	v_mov_b32_e32 v71, v127
	v_mov_b32_e32 v70, v127
	v_mov_b32_e32 v69, v127
	v_mov_b32_e32 v68, v127
	v_mov_b32_e32 v67, v127
	v_mov_b32_e32 v66, v127
	v_mov_b32_e32 v65, v127
	v_mov_b32_e32 v64, v127
	v_mov_b32_e32 v63, v127
	v_mov_b32_e32 v62, v127
	v_mov_b32_e32 v61, v127
	v_mov_b32_e32 v60, v127
	v_mov_b32_e32 v59, v127
	v_mov_b32_e32 v58, v127
	v_mov_b32_e32 v57, v127
	v_mov_b32_e32 v56, v127
	v_mov_b32_e32 v47, v127
	v_mov_b32_e32 v46, v127
	v_mov_b32_e32 v45, v127
	v_mov_b32_e32 v44, v127
	v_mov_b32_e32 v43, v127
	v_mov_b32_e32 v42, v127
	v_mov_b32_e32 v41, v127
	v_mov_b32_e32 v40, v127
	v_mov_b32_e32 v31, v127
	v_mov_b32_e32 v30, v127
	v_mov_b32_e32 v29, v127
	v_mov_b32_e32 v28, v127
	v_mov_b32_e32 v27, v127
	v_mov_b32_e32 v26, v127
	v_mov_b32_e32 v25, v127
	v_mov_b32_e32 v24, v127
	v_mov_b32_e32 v15, v127
	v_mov_b32_e32 v14, v127
	v_mov_b32_e32 v13, v127
	v_mov_b32_e32 v12, v127
	v_mov_b32_e32 v11, v127
	v_mov_b32_e32 v10, v127
	v_mov_b32_e32 v9, v127
	v_mov_b32_e32 v8, v127
	v_mov_b32_e32 v55, v127
	v_mov_b32_e32 v54, v127
	v_mov_b32_e32 v53, v127
	v_mov_b32_e32 v52, v127
	v_mov_b32_e32 v51, v127
	v_mov_b32_e32 v50, v127
	v_mov_b32_e32 v49, v127
	v_mov_b32_e32 v48, v127
	v_mov_b32_e32 v39, v127
	v_mov_b32_e32 v38, v127
	v_mov_b32_e32 v37, v127
	v_mov_b32_e32 v36, v127
	v_mov_b32_e32 v35, v127
	v_mov_b32_e32 v34, v127
	v_mov_b32_e32 v33, v127
	v_mov_b32_e32 v32, v127
	v_mov_b32_e32 v23, v127
	v_mov_b32_e32 v22, v127
	v_mov_b32_e32 v21, v127
	v_mov_b32_e32 v20, v127
	v_mov_b32_e32 v19, v127
	v_mov_b32_e32 v18, v127
	v_mov_b32_e32 v17, v127
	v_mov_b32_e32 v16, v127
	v_mov_b32_e32 v7, v127
	v_mov_b32_e32 v6, v127
	v_mov_b32_e32 v5, v127
	v_mov_b32_e32 v4, v127
	v_mov_b32_e32 v3, v127
	v_mov_b32_e32 v2, v127
	v_mov_b32_e32 v1, v127
	v_mov_b32_e32 v0, v127
	s_cbranch_vccnz .LBB0_697
	s_and_b64 s[54:55], s[8:9], exec
	s_cselect_b32 s73, s47, s53
	s_cselect_b32 s74, s46, s52
	s_cselect_b32 s75, s49, s51
	s_cselect_b32 s76, s48, s50
	s_add_u32 s77, s50, 0x100
	s_addc_u32 s78, s51, 0
	s_add_u32 s50, s52, 0x20080
	v_mov_b32_e32 v0, 0
	s_addc_u32 s51, s53, 0
	s_mov_b32 s52, 0

; #define PG8_BAR __builtin_amdgcn_s_barrier()
; template <class Epi, class Sched>
; __device__ __forceinline__ void gemm_phase(LAS unsigned char* lds, const Gemm g, const Sched& S, const Epi& E, const int wave_) {
;     ...
;         const bool has_next = S.next(ui + 1, nxt);
;         const char* nA = has_next ? (const char*)g.A + nxt.aoff : cA; const char* nB = has_next ? (const char*)g.Bt + nxt.boff : cB;
; #pragma unroll 1
;         for (int t = 0; t < nt; t += 2) {
;             if constexpr (Epi::HOOK) { if (t == 8 || t == 16) { E.hook(acc, cur, t >> 3, wr, wc, fr, fq); PG8_WAIT_V(0); } }
;             const bool last = (t == nt - 2);
;             const char* a1 = cA + (size_t)(t + 1) * kstep;
;             const char* a2 = last ? nA : cA + (size_t)(t + 2) * kstep; const char* b2 = last ? nB : cB + (size_t)(t + 2) * kstep;
;             const char* a3 = a2 + kstep; const char* b3 = b2 + kstep;
;             PG8_LDB(B0, 0, 0); PG8_LDB(B1, 0, 1); PG8_SCHED; PG8_LDA(At, 0, 0); PG8_STAGE(PG8_SA(1, 1), a1 + hstepA, voffA);
;             PG8_WAIT_V(8); PG8_WAIT_L(0); PG8_BAR; PG8_MMA(0, 0, At, B0); PG8_MMA(0, 1, At, B1); PG8_BAR; PG8_SCHED;
;             PG8_LDA(At, 0, 1); PG8_STAGE(PG8_SB(0, 0), b2, voffB); PG8_STAGE(PG8_SB(0, 1), b2 + hstepB, voffB); PG8_STAGE(PG8_SA(0, 0), a2, voffA);
;             PG8_WAIT_V(8); PG8_WAIT_L(0); PG8_BAR; PG8_MMA(1, 0, At, B0); PG8_MMA(1, 1, At, B1); PG8_BAR; PG8_SCHED;
;             PG8_LDB(B0, 1, 0); PG8_LDB(B1, 1, 1); PG8_SCHED; PG8_LDA(At, 1, 0); PG8_STAGE(PG8_SA(0, 1), a2 + hstepA, voffA);
;             PG8_WAIT_V(8); PG8_WAIT_L(0); PG8_BAR; PG8_MMA(0, 0, At, B0); PG8_MMA(0, 1, At, B1); PG8_BAR; PG8_SCHED;
;             PG8_LDA(At, 1, 1); PG8_STAGE(PG8_SB(1, 0), b3, voffB); PG8_STAGE(PG8_SB(1, 1), b3 + hstepB, voffB); PG8_STAGE(PG8_SA(1, 0), a3, voffA);
;             PG8_WAIT_V(8); PG8_WAIT_L(0); PG8_BAR; PG8_MMA(1, 0, At, B0); PG8_MMA(1, 1, At, B1); PG8_BAR; PG8_SCHED;
;         }
;         if (wr == 0) PG8_BAR;
;         E(acc, cur, wr, wc, fr, fq);
;         if (!has_next) break;
; #pragma unroll
;         for (int a = 0; a < 2; ++a)
; #pragma unroll
;             for (int b = 0; b < 2; ++b)
; #pragma unroll
;                 for (int m = 0; m < 4; ++m)
; #pragma unroll
;                     for (int n = 0; n < 2; ++n) acc[a][b][m][n] = (f32x4){0.f, 0.f, 0.f, 0.f};
;         cur = nxt; cA = nA; cB = nB; ++ui;
.LBB0_771:
	s_add_u32 s48, s28, s44
	s_addc_u32 s49, s29, s45
	s_add_u32 s50, s25, s46
	v_mov_b32_e32 v123, 0
	s_addc_u32 s51, s58, s47
	s_andn2_b64 vcc, exec, s[34:35]
	v_mov_b32_e32 v122, v123
	v_mov_b32_e32 v121, v123
	v_mov_b32_e32 v120, v123
	v_mov_b32_e32 v127, v123
	v_mov_b32_e32 v126, v123
	v_mov_b32_e32 v125, v123
	v_mov_b32_e32 v124, v123
	v_mov_b32_e32 v111, v123
	v_mov_b32_e32 v110, v123
	v_mov_b32_e32 v109, v123
	v_mov_b32_e32 v108, v123
	v_mov_b32_e32 v107, v123
	v_mov_b32_e32 v106, v123
	v_mov_b32_e32 v105, v123
	v_mov_b32_e32 v104, v123
	v_mov_b32_e32 v95, v123
	v_mov_b32_e32 v94, v123
	v_mov_b32_e32 v93, v123
	v_mov_b32_e32 v92, v123
	v_mov_b32_e32 v91, v123
	v_mov_b32_e32 v90, v123
	v_mov_b32_e32 v89, v123
	v_mov_b32_e32 v88, v123
	v_mov_b32_e32 v79, v123
	v_mov_b32_e32 v78, v123
	v_mov_b32_e32 v77, v123
	v_mov_b32_e32 v76, v123
	v_mov_b32_e32 v75, v123
	v_mov_b32_e32 v74, v123
	v_mov_b32_e32 v73, v123
	v_mov_b32_e32 v72, v123
	v_mov_b32_e32 v119, v123
	v_mov_b32_e32 v118, v123
	v_mov_b32_e32 v117, v123
	v_mov_b32_e32 v116, v123
	v_mov_b32_e32 v115, v123
	v_mov_b32_e32 v114, v123
	v_mov_b32_e32 v113, v123
	v_mov_b32_e32 v112, v123
	v_mov_b32_e32 v103, v123
	v_mov_b32_e32 v102, v123
	v_mov_b32_e32 v101, v123
	v_mov_b32_e32 v100, v123
	v_mov_b32_e32 v99, v123
	v_mov_b32_e32 v98, v123
	v_mov_b32_e32 v97, v123
	v_mov_b32_e32 v96, v123
	v_mov_b32_e32 v87, v123
	v_mov_b32_e32 v86, v123
	v_mov_b32_e32 v85, v123
	v_mov_b32_e32 v84, v123
	v_mov_b32_e32 v83, v123
	v_mov_b32_e32 v82, v123
	v_mov_b32_e32 v81, v123
	v_mov_b32_e32 v80, v123
	v_mov_b32_e32 v71, v123
	v_mov_b32_e32 v70, v123
	v_mov_b32_e32 v69, v123
	v_mov_b32_e32 v68, v123
	v_mov_b32_e32 v67, v123
	v_mov_b32_e32 v66, v123
	v_mov_b32_e32 v65, v123
	v_mov_b32_e32 v64, v123
	v_mov_b32_e32 v63, v123
	v_mov_b32_e32 v62, v123
	v_mov_b32_e32 v61, v123
	v_mov_b32_e32 v60, v123
	v_mov_b32_e32 v59, v123
	v_mov_b32_e32 v58, v123
	v_mov_b32_e32 v57, v123
	v_mov_b32_e32 v56, v123
	v_mov_b32_e32 v47, v123
	v_mov_b32_e32 v46, v123
	v_mov_b32_e32 v45, v123
	v_mov_b32_e32 v44, v123
	v_mov_b32_e32 v43, v123
	v_mov_b32_e32 v42, v123
	v_mov_b32_e32 v41, v123
	v_mov_b32_e32 v40, v123
	v_mov_b32_e32 v31, v123
	v_mov_b32_e32 v30, v123
	v_mov_b32_e32 v29, v123
	v_mov_b32_e32 v28, v123
	v_mov_b32_e32 v27, v123
	v_mov_b32_e32 v26, v123
	v_mov_b32_e32 v25, v123
	v_mov_b32_e32 v24, v123
	v_mov_b32_e32 v15, v123
	v_mov_b32_e32 v14, v123
	v_mov_b32_e32 v13, v123
	v_mov_b32_e32 v12, v123
	v_mov_b32_e32 v11, v123
	v_mov_b32_e32 v10, v123
	v_mov_b32_e32 v9, v123
	v_mov_b32_e32 v8, v123
	v_mov_b32_e32 v55, v123
	v_mov_b32_e32 v54, v123
	v_mov_b32_e32 v53, v123
	v_mov_b32_e32 v52, v123
	v_mov_b32_e32 v51, v123
	v_mov_b32_e32 v50, v123
	v_mov_b32_e32 v49, v123
	v_mov_b32_e32 v48, v123
	v_mov_b32_e32 v39, v123
	v_mov_b32_e32 v38, v123
	v_mov_b32_e32 v37, v123
	v_mov_b32_e32 v36, v123
	v_mov_b32_e32 v35, v123
	v_mov_b32_e32 v34, v123
	v_mov_b32_e32 v33, v123
	v_mov_b32_e32 v32, v123
	v_mov_b32_e32 v23, v123
	v_mov_b32_e32 v22, v123
	v_mov_b32_e32 v21, v123
	v_mov_b32_e32 v20, v123
	v_mov_b32_e32 v19, v123
	v_mov_b32_e32 v18, v123
	v_mov_b32_e32 v17, v123
	v_mov_b32_e32 v16, v123
	v_mov_b32_e32 v7, v123
	v_mov_b32_e32 v6, v123
	v_mov_b32_e32 v5, v123
	v_mov_b32_e32 v4, v123
	v_mov_b32_e32 v3, v123
	v_mov_b32_e32 v2, v123
	v_mov_b32_e32 v1, v123
	v_mov_b32_e32 v0, v123
	s_cbranch_vccnz .LBB0_774
	s_and_b64 s[56:57], s[6:7], exec
	s_cselect_b32 s41, s49, s55
	s_cselect_b32 s43, s48, s54
	s_cselect_b32 s75, s51, s53
	s_cselect_b32 s76, s50, s52
	s_add_u32 s77, s52, 0x100
	s_addc_u32 s78, s53, 0
	s_add_u32 s52, s54, 0x8080
	v_mov_b32_e32 v0, 0
	s_addc_u32 s53, s55, 0
	s_mov_b32 s54, 0

; #define PG8_BAR __builtin_amdgcn_s_barrier()
; template <class Epi, class Sched>
; __device__ __forceinline__ void gemm_phase(LAS unsigned char* lds, const Gemm g, const Sched& S, const Epi& E, const int wave_) {
;     ...
;         const bool has_next = S.next(ui + 1, nxt);
;         const char* nA = has_next ? (const char*)g.A + nxt.aoff : cA; const char* nB = has_next ? (const char*)g.Bt + nxt.boff : cB;
; #pragma unroll 1
;         for (int t = 0; t < nt; t += 2) {
;             if constexpr (Epi::HOOK) { if (t == 8 || t == 16) { E.hook(acc, cur, t >> 3, wr, wc, fr, fq); PG8_WAIT_V(0); } }
;             const bool last = (t == nt - 2);
;             const char* a1 = cA + (size_t)(t + 1) * kstep;
;             const char* a2 = last ? nA : cA + (size_t)(t + 2) * kstep; const char* b2 = last ? nB : cB + (size_t)(t + 2) * kstep;
;             const char* a3 = a2 + kstep; const char* b3 = b2 + kstep;
;             PG8_LDB(B0, 0, 0); PG8_LDB(B1, 0, 1); PG8_SCHED; PG8_LDA(At, 0, 0); PG8_STAGE(PG8_SA(1, 1), a1 + hstepA, voffA);
;             PG8_WAIT_V(8); PG8_WAIT_L(0); PG8_BAR; PG8_MMA(0, 0, At, B0); PG8_MMA(0, 1, At, B1); PG8_BAR; PG8_SCHED;
;             PG8_LDA(At, 0, 1); PG8_STAGE(PG8_SB(0, 0), b2, voffB); PG8_STAGE(PG8_SB(0, 1), b2 + hstepB, voffB); PG8_STAGE(PG8_SA(0, 0), a2, voffA);
;             PG8_WAIT_V(8); PG8_WAIT_L(0); PG8_BAR; PG8_MMA(1, 0, At, B0); PG8_MMA(1, 1, At, B1); PG8_BAR; PG8_SCHED;
;             PG8_LDB(B0, 1, 0); PG8_LDB(B1, 1, 1); PG8_SCHED; PG8_LDA(At, 1, 0); PG8_STAGE(PG8_SA(0, 1), a2 + hstepA, voffA);
;             PG8_WAIT_V(8); PG8_WAIT_L(0); PG8_BAR; PG8_MMA(0, 0, At, B0); PG8_MMA(0, 1, At, B1); PG8_BAR; PG8_SCHED;
;             PG8_LDA(At, 1, 1); PG8_STAGE(PG8_SB(1, 0), b3, voffB); PG8_STAGE(PG8_SB(1, 1), b3 + hstepB, voffB); PG8_STAGE(PG8_SA(1, 0), a3, voffA);
;             PG8_WAIT_V(8); PG8_WAIT_L(0); PG8_BAR; PG8_MMA(1, 0, At, B0); PG8_MMA(1, 1, At, B1); PG8_BAR; PG8_SCHED;
;         }
;         if (wr == 0) PG8_BAR;
;         E(acc, cur, wr, wc, fr, fq);
;         if (!has_next) break;
; #pragma unroll
;         for (int a = 0; a < 2; ++a)
; #pragma unroll
;             for (int b = 0; b < 2; ++b)
; #pragma unroll
;                 for (int m = 0; m < 4; ++m)
; #pragma unroll
;                     for (int n = 0; n < 2; ++n) acc[a][b][m][n] = (f32x4){0.f, 0.f, 0.f, 0.f};
;         cur = nxt; cA = nA; cB = nB; ++ui;
.LBB0_796:
	s_add_u32 s48, s25, s44
	s_addc_u32 s49, s58, s45
	s_add_u32 s50, s28, s46
	v_mov_b32_e32 v123, 0
	s_addc_u32 s51, s29, s47
	s_andn2_b64 vcc, exec, s[34:35]
	v_mov_b32_e32 v122, v123
	v_mov_b32_e32 v121, v123
	v_mov_b32_e32 v120, v123
	v_mov_b32_e32 v127, v123
	v_mov_b32_e32 v126, v123
	v_mov_b32_e32 v125, v123
	v_mov_b32_e32 v124, v123
	v_mov_b32_e32 v111, v123
	v_mov_b32_e32 v110, v123
	v_mov_b32_e32 v109, v123
	v_mov_b32_e32 v108, v123
	v_mov_b32_e32 v107, v123
	v_mov_b32_e32 v106, v123
	v_mov_b32_e32 v105, v123
	v_mov_b32_e32 v104, v123
	v_mov_b32_e32 v95, v123
	v_mov_b32_e32 v94, v123
	v_mov_b32_e32 v93, v123
	v_mov_b32_e32 v92, v123
	v_mov_b32_e32 v91, v123
	v_mov_b32_e32 v90, v123
	v_mov_b32_e32 v89, v123
	v_mov_b32_e32 v88, v123
	v_mov_b32_e32 v79, v123
	v_mov_b32_e32 v78, v123
	v_mov_b32_e32 v77, v123
	v_mov_b32_e32 v76, v123
	v_mov_b32_e32 v75, v123
	v_mov_b32_e32 v74, v123
	v_mov_b32_e32 v73, v123
	v_mov_b32_e32 v72, v123
	v_mov_b32_e32 v119, v123
	v_mov_b32_e32 v118, v123
	v_mov_b32_e32 v117, v123
	v_mov_b32_e32 v116, v123
	v_mov_b32_e32 v115, v123
	v_mov_b32_e32 v114, v123
	v_mov_b32_e32 v113, v123
	v_mov_b32_e32 v112, v123
	v_mov_b32_e32 v103, v123
	v_mov_b32_e32 v102, v123
	v_mov_b32_e32 v101, v123
	v_mov_b32_e32 v100, v123
	v_mov_b32_e32 v99, v123
	v_mov_b32_e32 v98, v123
	v_mov_b32_e32 v97, v123
	v_mov_b32_e32 v96, v123
	v_mov_b32_e32 v87, v123
	v_mov_b32_e32 v86, v123
	v_mov_b32_e32 v85, v123
	v_mov_b32_e32 v84, v123
	v_mov_b32_e32 v83, v123
	v_mov_b32_e32 v82, v123
	v_mov_b32_e32 v81, v123
	v_mov_b32_e32 v80, v123
	v_mov_b32_e32 v71, v123
	v_mov_b32_e32 v70, v123
	v_mov_b32_e32 v69, v123
	v_mov_b32_e32 v68, v123
	v_mov_b32_e32 v67, v123
	v_mov_b32_e32 v66, v123
	v_mov_b32_e32 v65, v123
	v_mov_b32_e32 v64, v123
	v_mov_b32_e32 v63, v123
	v_mov_b32_e32 v62, v123
	v_mov_b32_e32 v61, v123
	v_mov_b32_e32 v60, v123
	v_mov_b32_e32 v59, v123
	v_mov_b32_e32 v58, v123
	v_mov_b32_e32 v57, v123
	v_mov_b32_e32 v56, v123
	v_mov_b32_e32 v47, v123
	v_mov_b32_e32 v46, v123
	v_mov_b32_e32 v45, v123
	v_mov_b32_e32 v44, v123
	v_mov_b32_e32 v43, v123
	v_mov_b32_e32 v42, v123
	v_mov_b32_e32 v41, v123
	v_mov_b32_e32 v40, v123
	v_mov_b32_e32 v31, v123
	v_mov_b32_e32 v30, v123
	v_mov_b32_e32 v29, v123
	v_mov_b32_e32 v28, v123
	v_mov_b32_e32 v27, v123
	v_mov_b32_e32 v26, v123
	v_mov_b32_e32 v25, v123
	v_mov_b32_e32 v24, v123
	v_mov_b32_e32 v15, v123
	v_mov_b32_e32 v14, v123
	v_mov_b32_e32 v13, v123
	v_mov_b32_e32 v12, v123
	v_mov_b32_e32 v11, v123
	v_mov_b32_e32 v10, v123
	v_mov_b32_e32 v9, v123
	v_mov_b32_e32 v8, v123
	v_mov_b32_e32 v55, v123
	v_mov_b32_e32 v54, v123
	v_mov_b32_e32 v53, v123
	v_mov_b32_e32 v52, v123
	v_mov_b32_e32 v51, v123
	v_mov_b32_e32 v50, v123
	v_mov_b32_e32 v49, v123
	v_mov_b32_e32 v48, v123
	v_mov_b32_e32 v39, v123
	v_mov_b32_e32 v38, v123
	v_mov_b32_e32 v37, v123
	v_mov_b32_e32 v36, v123
	v_mov_b32_e32 v35, v123
	v_mov_b32_e32 v34, v123
	v_mov_b32_e32 v33, v123
	v_mov_b32_e32 v32, v123
	v_mov_b32_e32 v23, v123
	v_mov_b32_e32 v22, v123
	v_mov_b32_e32 v21, v123
	v_mov_b32_e32 v20, v123
	v_mov_b32_e32 v19, v123
	v_mov_b32_e32 v18, v123
	v_mov_b32_e32 v17, v123
	v_mov_b32_e32 v16, v123
	v_mov_b32_e32 v7, v123
	v_mov_b32_e32 v6, v123
	v_mov_b32_e32 v5, v123
	v_mov_b32_e32 v4, v123
	v_mov_b32_e32 v3, v123
	v_mov_b32_e32 v2, v123
	v_mov_b32_e32 v1, v123
	v_mov_b32_e32 v0, v123
	s_cbranch_vccnz .LBB0_799
	s_and_b64 s[56:57], s[6:7], exec
	s_cselect_b32 s41, s49, s55
	s_cselect_b32 s43, s48, s54
	s_cselect_b32 s72, s51, s53
	s_cselect_b32 s73, s50, s52
	s_add_u32 s74, s52, 0x100
	s_addc_u32 s75, s53, 0
	s_add_u32 s52, s54, 0x8080
	v_mov_b32_e32 v0, 0
	s_addc_u32 s53, s55, 0
	s_mov_b32 s54, 0

; #define PG8_BAR __builtin_amdgcn_s_barrier()
; template <class Epi, class Sched>
; __device__ __forceinline__ void gemm_phase(LAS unsigned char* lds, const Gemm g, const Sched& S, const Epi& E, const int wave_) {
;     ...
;         const bool has_next = S.next(ui + 1, nxt);
;         const char* nA = has_next ? (const char*)g.A + nxt.aoff : cA; const char* nB = has_next ? (const char*)g.Bt + nxt.boff : cB;
; #pragma unroll 1
;         for (int t = 0; t < nt; t += 2) {
;             if constexpr (Epi::HOOK) { if (t == 8 || t == 16) { E.hook(acc, cur, t >> 3, wr, wc, fr, fq); PG8_WAIT_V(0); } }
;             const bool last = (t == nt - 2);
;             const char* a1 = cA + (size_t)(t + 1) * kstep;
;             const char* a2 = last ? nA : cA + (size_t)(t + 2) * kstep; const char* b2 = last ? nB : cB + (size_t)(t + 2) * kstep;
;             const char* a3 = a2 + kstep; const char* b3 = b2 + kstep;
;             PG8_LDB(B0, 0, 0); PG8_LDB(B1, 0, 1); PG8_SCHED; PG8_LDA(At, 0, 0); PG8_STAGE(PG8_SA(1, 1), a1 + hstepA, voffA);
;             PG8_WAIT_V(8); PG8_WAIT_L(0); PG8_BAR; PG8_MMA(0, 0, At, B0); PG8_MMA(0, 1, At, B1); PG8_BAR; PG8_SCHED;
;             PG8_LDA(At, 0, 1); PG8_STAGE(PG8_SB(0, 0), b2, voffB); PG8_STAGE(PG8_SB(0, 1), b2 + hstepB, voffB); PG8_STAGE(PG8_SA(0, 0), a2, voffA);
;             PG8_WAIT_V(8); PG8_WAIT_L(0); PG8_BAR; PG8_MMA(1, 0, At, B0); PG8_MMA(1, 1, At, B1); PG8_BAR; PG8_SCHED;
;             PG8_LDB(B0, 1, 0); PG8_LDB(B1, 1, 1); PG8_SCHED; PG8_LDA(At, 1, 0); PG8_STAGE(PG8_SA(0, 1), a2 + hstepA, voffA);
;             PG8_WAIT_V(8); PG8_WAIT_L(0); PG8_BAR; PG8_MMA(0, 0, At, B0); PG8_MMA(0, 1, At, B1); PG8_BAR; PG8_SCHED;
;             PG8_LDA(At, 1, 1); PG8_STAGE(PG8_SB(1, 0), b3, voffB); PG8_STAGE(PG8_SB(1, 1), b3 + hstepB, voffB); PG8_STAGE(PG8_SA(1, 0), a3, voffA);
;             PG8_WAIT_V(8); PG8_WAIT_L(0); PG8_BAR; PG8_MMA(1, 0, At, B0); PG8_MMA(1, 1, At, B1); PG8_BAR; PG8_SCHED;
;         }
;         if (wr == 0) PG8_BAR;
;         E(acc, cur, wr, wc, fr, fq);
;         if (!has_next) break;
; #pragma unroll
;         for (int a = 0; a < 2; ++a)
; #pragma unroll
;             for (int b = 0; b < 2; ++b)
; #pragma unroll
;                 for (int m = 0; m < 4; ++m)
; #pragma unroll
;                     for (int n = 0; n < 2; ++n) acc[a][b][m][n] = (f32x4){0.f, 0.f, 0.f, 0.f};
;         cur = nxt; cA = nA; cB = nB; ++ui;
.LBB0_946:
	s_add_u32 s46, s6, s42
	s_addc_u32 s47, s7, s43
	s_add_u32 s48, s24, s44
	v_mov_b32_e32 v123, 0
	s_addc_u32 s49, s25, s45
	s_andn2_b64 vcc, exec, s[34:35]
	v_mov_b32_e32 v122, v123
	v_mov_b32_e32 v121, v123
	v_mov_b32_e32 v120, v123
	v_mov_b32_e32 v127, v123
	v_mov_b32_e32 v126, v123
	v_mov_b32_e32 v125, v123
	v_mov_b32_e32 v124, v123
	v_mov_b32_e32 v111, v123
	v_mov_b32_e32 v110, v123
	v_mov_b32_e32 v109, v123
	v_mov_b32_e32 v108, v123
	v_mov_b32_e32 v107, v123
	v_mov_b32_e32 v106, v123
	v_mov_b32_e32 v105, v123
	v_mov_b32_e32 v104, v123
	v_mov_b32_e32 v95, v123
	v_mov_b32_e32 v94, v123
	v_mov_b32_e32 v93, v123
	v_mov_b32_e32 v92, v123
	v_mov_b32_e32 v91, v123
	v_mov_b32_e32 v90, v123
	v_mov_b32_e32 v89, v123
	v_mov_b32_e32 v88, v123
	v_mov_b32_e32 v79, v123
	v_mov_b32_e32 v78, v123
	v_mov_b32_e32 v77, v123
	v_mov_b32_e32 v76, v123
	v_mov_b32_e32 v75, v123
	v_mov_b32_e32 v74, v123
	v_mov_b32_e32 v73, v123
	v_mov_b32_e32 v72, v123
	v_mov_b32_e32 v119, v123
	v_mov_b32_e32 v118, v123
	v_mov_b32_e32 v117, v123
	v_mov_b32_e32 v116, v123
	v_mov_b32_e32 v115, v123
	v_mov_b32_e32 v114, v123
	v_mov_b32_e32 v113, v123
	v_mov_b32_e32 v112, v123
	v_mov_b32_e32 v103, v123
	v_mov_b32_e32 v102, v123
	v_mov_b32_e32 v101, v123
	v_mov_b32_e32 v100, v123
	v_mov_b32_e32 v99, v123
	v_mov_b32_e32 v98, v123
	v_mov_b32_e32 v97, v123
	v_mov_b32_e32 v96, v123
	v_mov_b32_e32 v87, v123
	v_mov_b32_e32 v86, v123
	v_mov_b32_e32 v85, v123
	v_mov_b32_e32 v84, v123
	v_mov_b32_e32 v83, v123
	v_mov_b32_e32 v82, v123
	v_mov_b32_e32 v81, v123
	v_mov_b32_e32 v80, v123
	v_mov_b32_e32 v71, v123
	v_mov_b32_e32 v70, v123
	v_mov_b32_e32 v69, v123
	v_mov_b32_e32 v68, v123
	v_mov_b32_e32 v67, v123
	v_mov_b32_e32 v66, v123
	v_mov_b32_e32 v65, v123
	v_mov_b32_e32 v64, v123
	v_mov_b32_e32 v63, v123
	v_mov_b32_e32 v62, v123
	v_mov_b32_e32 v61, v123
	v_mov_b32_e32 v60, v123
	v_mov_b32_e32 v59, v123
	v_mov_b32_e32 v58, v123
	v_mov_b32_e32 v57, v123
	v_mov_b32_e32 v56, v123
	v_mov_b32_e32 v47, v123
	v_mov_b32_e32 v46, v123
	v_mov_b32_e32 v45, v123
	v_mov_b32_e32 v44, v123
	v_mov_b32_e32 v43, v123
	v_mov_b32_e32 v42, v123
	v_mov_b32_e32 v41, v123
	v_mov_b32_e32 v40, v123
	v_mov_b32_e32 v31, v123
	v_mov_b32_e32 v30, v123
	v_mov_b32_e32 v29, v123
	v_mov_b32_e32 v28, v123
	v_mov_b32_e32 v27, v123
	v_mov_b32_e32 v26, v123
	v_mov_b32_e32 v25, v123
	v_mov_b32_e32 v24, v123
	v_mov_b32_e32 v15, v123
	v_mov_b32_e32 v14, v123
	v_mov_b32_e32 v13, v123
	v_mov_b32_e32 v12, v123
	v_mov_b32_e32 v11, v123
	v_mov_b32_e32 v10, v123
	v_mov_b32_e32 v9, v123
	v_mov_b32_e32 v8, v123
	v_mov_b32_e32 v55, v123
	v_mov_b32_e32 v54, v123
	v_mov_b32_e32 v53, v123
	v_mov_b32_e32 v52, v123
	v_mov_b32_e32 v51, v123
	v_mov_b32_e32 v50, v123
	v_mov_b32_e32 v49, v123
	v_mov_b32_e32 v48, v123
	v_mov_b32_e32 v39, v123
	v_mov_b32_e32 v38, v123
	v_mov_b32_e32 v37, v123
	v_mov_b32_e32 v36, v123
	v_mov_b32_e32 v35, v123
	v_mov_b32_e32 v34, v123
	v_mov_b32_e32 v33, v123
	v_mov_b32_e32 v32, v123
	v_mov_b32_e32 v23, v123
	v_mov_b32_e32 v22, v123
	v_mov_b32_e32 v21, v123
	v_mov_b32_e32 v20, v123
	v_mov_b32_e32 v19, v123
	v_mov_b32_e32 v18, v123
	v_mov_b32_e32 v17, v123
	v_mov_b32_e32 v16, v123
	v_mov_b32_e32 v7, v123
	v_mov_b32_e32 v6, v123
	v_mov_b32_e32 v5, v123
	v_mov_b32_e32 v4, v123
	v_mov_b32_e32 v3, v123
	v_mov_b32_e32 v2, v123
	v_mov_b32_e32 v1, v123
	v_mov_b32_e32 v0, v123
	s_cbranch_vccnz .LBB0_949
	s_and_b64 s[56:57], s[4:5], exec
	s_cselect_b32 s39, s47, s55
	s_cselect_b32 s41, s46, s54
	s_cselect_b32 s73, s49, s53
	s_cselect_b32 s74, s48, s52
	s_add_u32 s75, s52, 0x100
	s_addc_u32 s76, s53, 0
	s_add_u32 s52, s54, 0x20080
	v_mov_b32_e32 v0, 0
	s_addc_u32 s53, s55, 0
	s_mov_b32 s54, 0

; #define PG8_BAR __builtin_amdgcn_s_barrier()
; template <class Epi, class Sched>
; __device__ __forceinline__ void gemm_phase(LAS unsigned char* lds, const Gemm g, const Sched& S, const Epi& E, const int wave_) {
;     ...
;         const bool has_next = S.next(ui + 1, nxt);
;         const char* nA = has_next ? (const char*)g.A + nxt.aoff : cA; const char* nB = has_next ? (const char*)g.Bt + nxt.boff : cB;
; #pragma unroll 1
;         for (int t = 0; t < nt; t += 2) {
;             if constexpr (Epi::HOOK) { if (t == 8 || t == 16) { E.hook(acc, cur, t >> 3, wr, wc, fr, fq); PG8_WAIT_V(0); } }
;             const bool last = (t == nt - 2);
;             const char* a1 = cA + (size_t)(t + 1) * kstep;
;             const char* a2 = last ? nA : cA + (size_t)(t + 2) * kstep; const char* b2 = last ? nB : cB + (size_t)(t + 2) * kstep;
;             const char* a3 = a2 + kstep; const char* b3 = b2 + kstep;
;             PG8_LDB(B0, 0, 0); PG8_LDB(B1, 0, 1); PG8_SCHED; PG8_LDA(At, 0, 0); PG8_STAGE(PG8_SA(1, 1), a1 + hstepA, voffA);
;             PG8_WAIT_V(8); PG8_WAIT_L(0); PG8_BAR; PG8_MMA(0, 0, At, B0); PG8_MMA(0, 1, At, B1); PG8_BAR; PG8_SCHED;
;             PG8_LDA(At, 0, 1); PG8_STAGE(PG8_SB(0, 0), b2, voffB); PG8_STAGE(PG8_SB(0, 1), b2 + hstepB, voffB); PG8_STAGE(PG8_SA(0, 0), a2, voffA);
;             PG8_WAIT_V(8); PG8_WAIT_L(0); PG8_BAR; PG8_MMA(1, 0, At, B0); PG8_MMA(1, 1, At, B1); PG8_BAR; PG8_SCHED;
;             PG8_LDB(B0, 1, 0); PG8_LDB(B1, 1, 1); PG8_SCHED; PG8_LDA(At, 1, 0); PG8_STAGE(PG8_SA(0, 1), a2 + hstepA, voffA);
;             PG8_WAIT_V(8); PG8_WAIT_L(0); PG8_BAR; PG8_MMA(0, 0, At, B0); PG8_MMA(0, 1, At, B1); PG8_BAR; PG8_SCHED;
;             PG8_LDA(At, 1, 1); PG8_STAGE(PG8_SB(1, 0), b3, voffB); PG8_STAGE(PG8_SB(1, 1), b3 + hstepB, voffB); PG8_STAGE(PG8_SA(1, 0), a3, voffA);
;             PG8_WAIT_V(8); PG8_WAIT_L(0); PG8_BAR; PG8_MMA(1, 0, At, B0); PG8_MMA(1, 1, At, B1); PG8_BAR; PG8_SCHED;
;         }
;         if (wr == 0) PG8_BAR;
;         E(acc, cur, wr, wc, fr, fq);
;         if (!has_next) break;
; #pragma unroll
;         for (int a = 0; a < 2; ++a)
; #pragma unroll
;             for (int b = 0; b < 2; ++b)
; #pragma unroll
;                 for (int m = 0; m < 4; ++m)
; #pragma unroll
;                     for (int n = 0; n < 2; ++n) acc[a][b][m][n] = (f32x4){0.f, 0.f, 0.f, 0.f};
;         cur = nxt; cA = nA; cB = nB; ++ui;
.LBB0_1023:
	s_add_u32 s46, s8, s42
	s_addc_u32 s47, s9, s43
	s_add_u32 s48, s24, s44
	v_mov_b32_e32 v123, 0
	s_addc_u32 s49, s25, s45
	s_andn2_b64 vcc, exec, s[34:35]
	v_mov_b32_e32 v122, v123
	v_mov_b32_e32 v121, v123
	v_mov_b32_e32 v120, v123
	v_mov_b32_e32 v127, v123
	v_mov_b32_e32 v126, v123
	v_mov_b32_e32 v125, v123
	v_mov_b32_e32 v124, v123
	v_mov_b32_e32 v111, v123
	v_mov_b32_e32 v110, v123
	v_mov_b32_e32 v109, v123
	v_mov_b32_e32 v108, v123
	v_mov_b32_e32 v107, v123
	v_mov_b32_e32 v106, v123
	v_mov_b32_e32 v105, v123
	v_mov_b32_e32 v104, v123
	v_mov_b32_e32 v95, v123
	v_mov_b32_e32 v94, v123
	v_mov_b32_e32 v93, v123
	v_mov_b32_e32 v92, v123
	v_mov_b32_e32 v91, v123
	v_mov_b32_e32 v90, v123
	v_mov_b32_e32 v89, v123
	v_mov_b32_e32 v88, v123
	v_mov_b32_e32 v79, v123
	v_mov_b32_e32 v78, v123
	v_mov_b32_e32 v77, v123
	v_mov_b32_e32 v76, v123
	v_mov_b32_e32 v75, v123
	v_mov_b32_e32 v74, v123
	v_mov_b32_e32 v73, v123
	v_mov_b32_e32 v72, v123
	v_mov_b32_e32 v119, v123
	v_mov_b32_e32 v118, v123
	v_mov_b32_e32 v117, v123
	v_mov_b32_e32 v116, v123
	v_mov_b32_e32 v115, v123
	v_mov_b32_e32 v114, v123
	v_mov_b32_e32 v113, v123
	v_mov_b32_e32 v112, v123
	v_mov_b32_e32 v103, v123
	v_mov_b32_e32 v102, v123
	v_mov_b32_e32 v101, v123
	v_mov_b32_e32 v100, v123
	v_mov_b32_e32 v99, v123
	v_mov_b32_e32 v98, v123
	v_mov_b32_e32 v97, v123
	v_mov_b32_e32 v96, v123
	v_mov_b32_e32 v87, v123
	v_mov_b32_e32 v86, v123
	v_mov_b32_e32 v85, v123
	v_mov_b32_e32 v84, v123
	v_mov_b32_e32 v83, v123
	v_mov_b32_e32 v82, v123
	v_mov_b32_e32 v81, v123
	v_mov_b32_e32 v80, v123
	v_mov_b32_e32 v71, v123
	v_mov_b32_e32 v70, v123
	v_mov_b32_e32 v69, v123
	v_mov_b32_e32 v68, v123
	v_mov_b32_e32 v67, v123
	v_mov_b32_e32 v66, v123
	v_mov_b32_e32 v65, v123
	v_mov_b32_e32 v64, v123
	v_mov_b32_e32 v63, v123
	v_mov_b32_e32 v62, v123
	v_mov_b32_e32 v61, v123
	v_mov_b32_e32 v60, v123
	v_mov_b32_e32 v59, v123
	v_mov_b32_e32 v58, v123
	v_mov_b32_e32 v57, v123
	v_mov_b32_e32 v56, v123
	v_mov_b32_e32 v47, v123
	v_mov_b32_e32 v46, v123
	v_mov_b32_e32 v45, v123
	v_mov_b32_e32 v44, v123
	v_mov_b32_e32 v43, v123
	v_mov_b32_e32 v42, v123
	v_mov_b32_e32 v41, v123
	v_mov_b32_e32 v40, v123
	v_mov_b32_e32 v31, v123
	v_mov_b32_e32 v30, v123
	v_mov_b32_e32 v29, v123
	v_mov_b32_e32 v28, v123
	v_mov_b32_e32 v27, v123
	v_mov_b32_e32 v26, v123
	v_mov_b32_e32 v25, v123
	v_mov_b32_e32 v24, v123
	v_mov_b32_e32 v15, v123
	v_mov_b32_e32 v14, v123
	v_mov_b32_e32 v13, v123
	v_mov_b32_e32 v12, v123
	v_mov_b32_e32 v11, v123
	v_mov_b32_e32 v10, v123
	v_mov_b32_e32 v9, v123
	v_mov_b32_e32 v8, v123
	v_mov_b32_e32 v55, v123
	v_mov_b32_e32 v54, v123
	v_mov_b32_e32 v53, v123
	v_mov_b32_e32 v52, v123
	v_mov_b32_e32 v51, v123
	v_mov_b32_e32 v50, v123
	v_mov_b32_e32 v49, v123
	v_mov_b32_e32 v48, v123
	v_mov_b32_e32 v39, v123
	v_mov_b32_e32 v38, v123
	v_mov_b32_e32 v37, v123
	v_mov_b32_e32 v36, v123
	v_mov_b32_e32 v35, v123
	v_mov_b32_e32 v34, v123
	v_mov_b32_e32 v33, v123
	v_mov_b32_e32 v32, v123
	v_mov_b32_e32 v23, v123
	v_mov_b32_e32 v22, v123
	v_mov_b32_e32 v21, v123
	v_mov_b32_e32 v20, v123
	v_mov_b32_e32 v19, v123
	v_mov_b32_e32 v18, v123
	v_mov_b32_e32 v17, v123
	v_mov_b32_e32 v16, v123
	v_mov_b32_e32 v7, v123
	v_mov_b32_e32 v6, v123
	v_mov_b32_e32 v5, v123
	v_mov_b32_e32 v4, v123
	v_mov_b32_e32 v3, v123
	v_mov_b32_e32 v2, v123
	v_mov_b32_e32 v1, v123
	v_mov_b32_e32 v0, v123
	s_cbranch_vccnz .LBB0_1032
	s_and_b64 s[54:55], s[4:5], exec
	s_cselect_b32 s89, s47, s51
	s_cselect_b32 s90, s46, s50
	s_cselect_b32 s91, s49, s53
	s_cselect_b32 s92, s48, s52
	s_lshl_b32 s54, s88, 8
	s_ashr_i32 s55, s54, 31
	s_add_u32 s93, s52, 0x100
	s_addc_u32 s94, s53, 0
	s_lshl_b64 s[52:53], s[54:55], 1
	v_lshl_add_u32 v2, s87, 8, v191
	v_mov_b64_e32 v[0:1], s[52:53]
	v_mad_i64_i32 v[0:1], s[52:53], v2, s70, v[0:1]
	v_lshl_add_u64 v[182:183], v[176:177], 0, v[0:1]
	v_mov_b32_e32 v0, 0
	s_mov_b32 s56, 0
	v_mov_b32_e32 v1, v0
	v_mov_b32_e32 v2, v0
	s_cmp_lt_i32 s56, 16
	s_cbranch_scc0 .LBB0_1031

; #define PG8_BAR __builtin_amdgcn_s_barrier()
; template <class Epi, class Sched>
; __device__ __forceinline__ void gemm_phase(LAS unsigned char* lds, const Gemm g, const Sched& S, const Epi& E, const int wave_) {
;     ...
;         const bool has_next = S.next(ui + 1, nxt);
;         const char* nA = has_next ? (const char*)g.A + nxt.aoff : cA; const char* nB = has_next ? (const char*)g.Bt + nxt.boff : cB;
; #pragma unroll 1
;         for (int t = 0; t < nt; t += 2) {
;             if constexpr (Epi::HOOK) { if (t == 8 || t == 16) { E.hook(acc, cur, t >> 3, wr, wc, fr, fq); PG8_WAIT_V(0); } }
;             const bool last = (t == nt - 2);
;             const char* a1 = cA + (size_t)(t + 1) * kstep;
;             const char* a2 = last ? nA : cA + (size_t)(t + 2) * kstep; const char* b2 = last ? nB : cB + (size_t)(t + 2) * kstep;
;             const char* a3 = a2 + kstep; const char* b3 = b2 + kstep;
;             PG8_LDB(B0, 0, 0); PG8_LDB(B1, 0, 1); PG8_SCHED; PG8_LDA(At, 0, 0); PG8_STAGE(PG8_SA(1, 1), a1 + hstepA, voffA);
;             PG8_WAIT_V(8); PG8_WAIT_L(0); PG8_BAR; PG8_MMA(0, 0, At, B0); PG8_MMA(0, 1, At, B1); PG8_BAR; PG8_SCHED;
;             PG8_LDA(At, 0, 1); PG8_STAGE(PG8_SB(0, 0), b2, voffB); PG8_STAGE(PG8_SB(0, 1), b2 + hstepB, voffB); PG8_STAGE(PG8_SA(0, 0), a2, voffA);
;             PG8_WAIT_V(8); PG8_WAIT_L(0); PG8_BAR; PG8_MMA(1, 0, At, B0); PG8_MMA(1, 1, At, B1); PG8_BAR; PG8_SCHED;
;             PG8_LDB(B0, 1, 0); PG8_LDB(B1, 1, 1); PG8_SCHED; PG8_LDA(At, 1, 0); PG8_STAGE(PG8_SA(0, 1), a2 + hstepA, voffA);
;             PG8_WAIT_V(8); PG8_WAIT_L(0); PG8_BAR; PG8_MMA(0, 0, At, B0); PG8_MMA(0, 1, At, B1); PG8_BAR; PG8_SCHED;
;             PG8_LDA(At, 1, 1); PG8_STAGE(PG8_SB(1, 0), b3, voffB); PG8_STAGE(PG8_SB(1, 1), b3 + hstepB, voffB); PG8_STAGE(PG8_SA(1, 0), a3, voffA);
;             PG8_WAIT_V(8); PG8_WAIT_L(0); PG8_BAR; PG8_MMA(1, 0, At, B0); PG8_MMA(1, 1, At, B1); PG8_BAR; PG8_SCHED;
;         }
;         if (wr == 0) PG8_BAR;
;         E(acc, cur, wr, wc, fr, fq);
;         if (!has_next) break;
; #pragma unroll
;         for (int a = 0; a < 2; ++a)
; #pragma unroll
;             for (int b = 0; b < 2; ++b)
; #pragma unroll
;                 for (int m = 0; m < 4; ++m)
; #pragma unroll
;                     for (int n = 0; n < 2; ++n) acc[a][b][m][n] = (f32x4){0.f, 0.f, 0.f, 0.f};
;         cur = nxt; cA = nA; cB = nB; ++ui;
.LBB0_1107:
	s_add_u32 s44, s24, s40
	s_addc_u32 s45, s25, s41
	s_add_u32 s46, s54, s42
	v_mov_b32_e32 v123, 0
	s_addc_u32 s47, s55, s43
	s_andn2_b64 vcc, exec, s[28:29]
	v_mov_b32_e32 v122, v123
	v_mov_b32_e32 v121, v123
	v_mov_b32_e32 v120, v123
	v_mov_b32_e32 v127, v123
	v_mov_b32_e32 v126, v123
	v_mov_b32_e32 v125, v123
	v_mov_b32_e32 v124, v123
	v_mov_b32_e32 v111, v123
	v_mov_b32_e32 v110, v123
	v_mov_b32_e32 v109, v123
	v_mov_b32_e32 v108, v123
	v_mov_b32_e32 v107, v123
	v_mov_b32_e32 v106, v123
	v_mov_b32_e32 v105, v123
	v_mov_b32_e32 v104, v123
	v_mov_b32_e32 v95, v123
	v_mov_b32_e32 v94, v123
	v_mov_b32_e32 v93, v123
	v_mov_b32_e32 v92, v123
	v_mov_b32_e32 v91, v123
	v_mov_b32_e32 v90, v123
	v_mov_b32_e32 v89, v123
	v_mov_b32_e32 v88, v123
	v_mov_b32_e32 v79, v123
	v_mov_b32_e32 v78, v123
	v_mov_b32_e32 v77, v123
	v_mov_b32_e32 v76, v123
	v_mov_b32_e32 v75, v123
	v_mov_b32_e32 v74, v123
	v_mov_b32_e32 v73, v123
	v_mov_b32_e32 v72, v123
	v_mov_b32_e32 v119, v123
	v_mov_b32_e32 v118, v123
	v_mov_b32_e32 v117, v123
	v_mov_b32_e32 v116, v123
	v_mov_b32_e32 v115, v123
	v_mov_b32_e32 v114, v123
	v_mov_b32_e32 v113, v123
	v_mov_b32_e32 v112, v123
	v_mov_b32_e32 v103, v123
	v_mov_b32_e32 v102, v123
	v_mov_b32_e32 v101, v123
	v_mov_b32_e32 v100, v123
	v_mov_b32_e32 v99, v123
	v_mov_b32_e32 v98, v123
	v_mov_b32_e32 v97, v123
	v_mov_b32_e32 v96, v123
	v_mov_b32_e32 v87, v123
	v_mov_b32_e32 v86, v123
	v_mov_b32_e32 v85, v123
	v_mov_b32_e32 v84, v123
	v_mov_b32_e32 v83, v123
	v_mov_b32_e32 v82, v123
	v_mov_b32_e32 v81, v123
	v_mov_b32_e32 v80, v123
	v_mov_b32_e32 v71, v123
	v_mov_b32_e32 v70, v123
	v_mov_b32_e32 v69, v123
	v_mov_b32_e32 v68, v123
	v_mov_b32_e32 v67, v123
	v_mov_b32_e32 v66, v123
	v_mov_b32_e32 v65, v123
	v_mov_b32_e32 v64, v123
	v_mov_b32_e32 v63, v123
	v_mov_b32_e32 v62, v123
	v_mov_b32_e32 v61, v123
	v_mov_b32_e32 v60, v123
	v_mov_b32_e32 v59, v123
	v_mov_b32_e32 v58, v123
	v_mov_b32_e32 v57, v123
	v_mov_b32_e32 v56, v123
	v_mov_b32_e32 v47, v123
	v_mov_b32_e32 v46, v123
	v_mov_b32_e32 v45, v123
	v_mov_b32_e32 v44, v123
	v_mov_b32_e32 v43, v123
	v_mov_b32_e32 v42, v123
	v_mov_b32_e32 v41, v123
	v_mov_b32_e32 v40, v123
	v_mov_b32_e32 v31, v123
	v_mov_b32_e32 v30, v123
	v_mov_b32_e32 v29, v123
	v_mov_b32_e32 v28, v123
	v_mov_b32_e32 v27, v123
	v_mov_b32_e32 v26, v123
	v_mov_b32_e32 v25, v123
	v_mov_b32_e32 v24, v123
	v_mov_b32_e32 v15, v123
	v_mov_b32_e32 v14, v123
	v_mov_b32_e32 v13, v123
	v_mov_b32_e32 v12, v123
	v_mov_b32_e32 v11, v123
	v_mov_b32_e32 v10, v123
	v_mov_b32_e32 v9, v123
	v_mov_b32_e32 v8, v123
	v_mov_b32_e32 v55, v123
	v_mov_b32_e32 v54, v123
	v_mov_b32_e32 v53, v123
	v_mov_b32_e32 v52, v123
	v_mov_b32_e32 v51, v123
	v_mov_b32_e32 v50, v123
	v_mov_b32_e32 v49, v123
	v_mov_b32_e32 v48, v123
	v_mov_b32_e32 v39, v123
	v_mov_b32_e32 v38, v123
	v_mov_b32_e32 v37, v123
	v_mov_b32_e32 v36, v123
	v_mov_b32_e32 v35, v123
	v_mov_b32_e32 v34, v123
	v_mov_b32_e32 v33, v123
	v_mov_b32_e32 v32, v123
	v_mov_b32_e32 v23, v123
	v_mov_b32_e32 v22, v123
	v_mov_b32_e32 v21, v123
	v_mov_b32_e32 v20, v123
	v_mov_b32_e32 v19, v123
	v_mov_b32_e32 v18, v123
	v_mov_b32_e32 v17, v123
	v_mov_b32_e32 v16, v123
	v_mov_b32_e32 v7, v123
	v_mov_b32_e32 v6, v123
	v_mov_b32_e32 v5, v123
	v_mov_b32_e32 v4, v123
	v_mov_b32_e32 v3, v123
	v_mov_b32_e32 v2, v123
	v_mov_b32_e32 v1, v123
	v_mov_b32_e32 v0, v123
	s_cbranch_vccnz .LBB0_1110
	s_and_b64 s[52:53], s[4:5], exec
	s_cselect_b32 s37, s45, s51
	s_cselect_b32 s39, s44, s50
	s_cselect_b32 s68, s47, s49
	s_cselect_b32 s69, s46, s48
	s_add_u32 s70, s48, 0x100
	s_addc_u32 s71, s49, 0
	s_add_u32 s48, s50, 0x40080
	v_mov_b32_e32 v0, 0
	s_addc_u32 s49, s51, 0
	s_mov_b32 s50, 0

; #define PG8_BAR __builtin_amdgcn_s_barrier()
; template <class Epi, class Sched>
; __device__ __forceinline__ void gemm_phase(LAS unsigned char* lds, const Gemm g, const Sched& S, const Epi& E, const int wave_) {
;     ...
;         const bool has_next = S.next(ui + 1, nxt);
;         const char* nA = has_next ? (const char*)g.A + nxt.aoff : cA; const char* nB = has_next ? (const char*)g.Bt + nxt.boff : cB;
; #pragma unroll 1
;         for (int t = 0; t < nt; t += 2) {
;             if constexpr (Epi::HOOK) { if (t == 8 || t == 16) { E.hook(acc, cur, t >> 3, wr, wc, fr, fq); PG8_WAIT_V(0); } }
;             const bool last = (t == nt - 2);
;             const char* a1 = cA + (size_t)(t + 1) * kstep;
;             const char* a2 = last ? nA : cA + (size_t)(t + 2) * kstep; const char* b2 = last ? nB : cB + (size_t)(t + 2) * kstep;
;             const char* a3 = a2 + kstep; const char* b3 = b2 + kstep;
;             PG8_LDB(B0, 0, 0); PG8_LDB(B1, 0, 1); PG8_SCHED; PG8_LDA(At, 0, 0); PG8_STAGE(PG8_SA(1, 1), a1 + hstepA, voffA);
;             PG8_WAIT_V(8); PG8_WAIT_L(0); PG8_BAR; PG8_MMA(0, 0, At, B0); PG8_MMA(0, 1, At, B1); PG8_BAR; PG8_SCHED;
;             PG8_LDA(At, 0, 1); PG8_STAGE(PG8_SB(0, 0), b2, voffB); PG8_STAGE(PG8_SB(0, 1), b2 + hstepB, voffB); PG8_STAGE(PG8_SA(0, 0), a2, voffA);
;             PG8_WAIT_V(8); PG8_WAIT_L(0); PG8_BAR; PG8_MMA(1, 0, At, B0); PG8_MMA(1, 1, At, B1); PG8_BAR; PG8_SCHED;
;             PG8_LDB(B0, 1, 0); PG8_LDB(B1, 1, 1); PG8_SCHED; PG8_LDA(At, 1, 0); PG8_STAGE(PG8_SA(0, 1), a2 + hstepA, voffA);
;             PG8_WAIT_V(8); PG8_WAIT_L(0); PG8_BAR; PG8_MMA(0, 0, At, B0); PG8_MMA(0, 1, At, B1); PG8_BAR; PG8_SCHED;
;             PG8_LDA(At, 1, 1); PG8_STAGE(PG8_SB(1, 0), b3, voffB); PG8_STAGE(PG8_SB(1, 1), b3 + hstepB, voffB); PG8_STAGE(PG8_SA(1, 0), a3, voffA);
;             PG8_WAIT_V(8); PG8_WAIT_L(0); PG8_BAR; PG8_MMA(1, 0, At, B0); PG8_MMA(1, 1, At, B1); PG8_BAR; PG8_SCHED;
;         }
;         if (wr == 0) PG8_BAR;
;         E(acc, cur, wr, wc, fr, fq);
;         if (!has_next) break;
; #pragma unroll
;         for (int a = 0; a < 2; ++a)
; #pragma unroll
;             for (int b = 0; b < 2; ++b)
; #pragma unroll
;                 for (int m = 0; m < 4; ++m)
; #pragma unroll
;                     for (int n = 0; n < 2; ++n) acc[a][b][m][n] = (f32x4){0.f, 0.f, 0.f, 0.f};
;         cur = nxt; cA = nA; cB = nB; ++ui;
.LBB0_1178:
	s_andn2_b64 vcc, exec, s[42:43]
	s_add_u32 s30, s3, s18
	s_addc_u32 s31, s44, s19
	v_cndmask_b32_e64 v0, 0, 1, s[42:43]
	s_add_u32 s34, s45, s28
	v_mov_b32_e32 v127, 0
	v_cmp_ne_u32_e64 s[8:9], 1, v0
	s_addc_u32 s35, s46, s29
	s_and_b64 vcc, exec, s[6:7]
	v_mov_b32_e32 v126, v127
	v_mov_b32_e32 v125, v127
	v_mov_b32_e32 v124, v127
	v_mov_b32_e32 v123, v127
	v_mov_b32_e32 v122, v127
	v_mov_b32_e32 v121, v127
	v_mov_b32_e32 v120, v127
	v_mov_b32_e32 v111, v127
	v_mov_b32_e32 v110, v127
	v_mov_b32_e32 v109, v127
	v_mov_b32_e32 v108, v127
	v_mov_b32_e32 v107, v127
	v_mov_b32_e32 v106, v127
	v_mov_b32_e32 v105, v127
	v_mov_b32_e32 v104, v127
	v_mov_b32_e32 v95, v127
	v_mov_b32_e32 v94, v127
	v_mov_b32_e32 v93, v127
	v_mov_b32_e32 v92, v127
	v_mov_b32_e32 v91, v127
	v_mov_b32_e32 v90, v127
	v_mov_b32_e32 v89, v127
	v_mov_b32_e32 v88, v127
	v_mov_b32_e32 v79, v127
	v_mov_b32_e32 v78, v127
	v_mov_b32_e32 v77, v127
	v_mov_b32_e32 v76, v127
	v_mov_b32_e32 v75, v127
	v_mov_b32_e32 v74, v127
	v_mov_b32_e32 v73, v127
	v_mov_b32_e32 v72, v127
	v_mov_b32_e32 v119, v127
	v_mov_b32_e32 v118, v127
	v_mov_b32_e32 v117, v127
	v_mov_b32_e32 v116, v127
	v_mov_b32_e32 v115, v127
	v_mov_b32_e32 v114, v127
	v_mov_b32_e32 v113, v127
	v_mov_b32_e32 v112, v127
	v_mov_b32_e32 v103, v127
	v_mov_b32_e32 v102, v127
	v_mov_b32_e32 v101, v127
	v_mov_b32_e32 v100, v127
	v_mov_b32_e32 v99, v127
	v_mov_b32_e32 v98, v127
	v_mov_b32_e32 v97, v127
	v_mov_b32_e32 v96, v127
	v_mov_b32_e32 v87, v127
	v_mov_b32_e32 v86, v127
	v_mov_b32_e32 v85, v127
	v_mov_b32_e32 v84, v127
	v_mov_b32_e32 v83, v127
	v_mov_b32_e32 v82, v127
	v_mov_b32_e32 v81, v127
	v_mov_b32_e32 v80, v127
	v_mov_b32_e32 v71, v127
	v_mov_b32_e32 v70, v127
	v_mov_b32_e32 v69, v127
	v_mov_b32_e32 v68, v127
	v_mov_b32_e32 v67, v127
	v_mov_b32_e32 v66, v127
	v_mov_b32_e32 v65, v127
	v_mov_b32_e32 v64, v127
	v_mov_b32_e32 v63, v127
	v_mov_b32_e32 v62, v127
	v_mov_b32_e32 v61, v127
	v_mov_b32_e32 v60, v127
	v_mov_b32_e32 v59, v127
	v_mov_b32_e32 v58, v127
	v_mov_b32_e32 v57, v127
	v_mov_b32_e32 v56, v127
	v_mov_b32_e32 v47, v127
	v_mov_b32_e32 v46, v127
	v_mov_b32_e32 v45, v127
	v_mov_b32_e32 v44, v127
	v_mov_b32_e32 v43, v127
	v_mov_b32_e32 v42, v127
	v_mov_b32_e32 v41, v127
	v_mov_b32_e32 v40, v127
	v_mov_b32_e32 v31, v127
	v_mov_b32_e32 v30, v127
	v_mov_b32_e32 v29, v127
	v_mov_b32_e32 v28, v127
	v_mov_b32_e32 v27, v127
	v_mov_b32_e32 v26, v127
	v_mov_b32_e32 v25, v127
	v_mov_b32_e32 v24, v127
	v_mov_b32_e32 v15, v127
	v_mov_b32_e32 v14, v127
	v_mov_b32_e32 v13, v127
	v_mov_b32_e32 v12, v127
	v_mov_b32_e32 v11, v127
	v_mov_b32_e32 v10, v127
	v_mov_b32_e32 v9, v127
	v_mov_b32_e32 v8, v127
	v_mov_b32_e32 v55, v127
	v_mov_b32_e32 v54, v127
	v_mov_b32_e32 v53, v127
	v_mov_b32_e32 v52, v127
	v_mov_b32_e32 v51, v127
	v_mov_b32_e32 v50, v127
	v_mov_b32_e32 v49, v127
	v_mov_b32_e32 v48, v127
	v_mov_b32_e32 v39, v127
	v_mov_b32_e32 v38, v127
	v_mov_b32_e32 v37, v127
	v_mov_b32_e32 v36, v127
	v_mov_b32_e32 v35, v127
	v_mov_b32_e32 v34, v127
	v_mov_b32_e32 v33, v127
	v_mov_b32_e32 v32, v127
	v_mov_b32_e32 v23, v127
	v_mov_b32_e32 v22, v127
	v_mov_b32_e32 v21, v127
	v_mov_b32_e32 v20, v127
	v_mov_b32_e32 v19, v127
	v_mov_b32_e32 v18, v127
	v_mov_b32_e32 v17, v127
	v_mov_b32_e32 v16, v127
	v_mov_b32_e32 v7, v127
	v_mov_b32_e32 v6, v127
	s_waitcnt lgkmcnt(0)
	v_mov_b32_e32 v5, v127
	v_mov_b32_e32 v4, v127
	v_mov_b32_e32 v3, v127
	v_mov_b32_e32 v2, v127
	v_mov_b32_e32 v1, v127
	v_mov_b32_e32 v0, v127
	s_cbranch_vccnz .LBB0_1181
	s_and_b64 s[42:43], s[42:43], exec
	s_cselect_b32 s37, s31, s41
	s_cselect_b32 s59, s30, s40
	s_cselect_b32 s60, s35, s39
	s_cselect_b32 s61, s34, s38
	s_add_u32 s62, s38, 0x100
	s_addc_u32 s63, s39, 0
	s_add_u32 s38, s40, 0x40080
	v_mov_b32_e32 v0, 0
	s_addc_u32 s39, s41, 0
	s_mov_b32 s40, 0
	v_mov_b32_e32 v1, v0
	v_mov_b32_e32 v2, v0
	v_mov_b32_e32 v3, v0
	v_mov_b32_e32 v4, v0
	v_mov_b32_e32 v5, v0
